# attnA rewritten: two query tiles per wave as interleaved streams, K/V by LDS-DMA, sequence epilogue transposed through LDS so stores and merge loads are full 128-byte rows
# speedup vs baseline: 1.1187x; 1.0113x over previous
; #define LAS __attribute__((address_space(3)))
; __device__ __forceinline__ int tidx() { int t = threadIdx.x; asm volatile("" : "+v"(t)); return t; }
; template <bool KLDS>
; __device__ __forceinline__ void attn_step(const bf16x8 (&kf)[4], LAS const unsigned char* kb, const bf16x8 (&vf)[2][2], const bf16x8 (&qf)[4], f32x16& o0, f32x16& o1, float& m, float& l, int lane, int maskmode) {
;     ...
;         for (int i = 0; i < 16; ++i) { const int kr = (i & 3) + 8 * (i >> 2) + 4 * h; const bool ok = (maskmode == 1) ? (kr >= ql) : (kr <= ql); S[i] = ok ? S[i] : -1e30f; }
; __device__ __forceinline__ void attnA_unit(const Args& a, int unit, LAS unsigned char* lds) {
;     const int tid = tidx(), wid = __builtin_amdgcn_readfirstlane(tid >> 6), lane = tid & 63, ql = lane & 31, h = lane >> 5;
;     const int b = unit / 24, rem = unit % 24, hh = rem >> 2, blk = rem & 3;
;     const bf16_t* P = (const bf16_t*)(a.ws + WS_P);
;     bf16_t* OA = (bf16_t*)(a.ws + OFF_OA); float* LSE = (float*)(a.ws + OFF_LSE); bf16_t* MIX = (bf16_t*)(a.ws + WS_MIX);
;     LAS unsigned char* wl = lds + wid * 8192;
;     const unsigned char* kbase = (const unsigned char*)(P + (size_t)b * SEQ * PW + 384 + 64 * hh);
;     const unsigned char* vbase = (const unsigned char*)(P + (size_t)b * SEQ * PW + 768 + 64 * hh);
.LBB0_261:
	v_writelane_b32 v255, s0, 36
	s_lshl_b32 s0, s0, 5
	s_add_i32 s0, s0, s17
	s_mul_hi_i32 s2, s0, 0x2aaaaaab
	v_mov_b32_e32 v2, v225
	s_lshr_b32 s3, s2, 31
	s_ashr_i32 s2, s2, 2
	s_add_i32 s2, s2, s3
	v_readfirstlane_b32 s1, v2
	s_ashr_i32 s1, s1, 6
	s_mul_i32 s3, s2, 24
	s_sub_i32 s6, s0, s3
	s_lshl_b32 s3, s1, 14
	s_add_i32 s8, s3, 0
	s_ashr_i32 s3, s2, 31
	s_ashr_i32 s0, s6, 2
	s_lshl_b64 s[76:77], s[2:3], 11
	s_mul_hi_i32 s3, s2, 0xa00000
	s_mul_i32 s2, s2, 0xa00000
	s_add_u32 s4, s26, s2
	s_addc_u32 s5, s27, s3
	s_lshl_b32 s2, s0, 6
	s_ashr_i32 s3, s2, 31
	s_lshl_b64 s[2:3], s[2:3], 1
	s_add_u32 s4, s4, s2
	s_addc_u32 s5, s5, s3
	s_add_u32 s98, s4, 0x300
	s_addc_u32 s99, s5, 0
	v_writelane_b32 v255, s98, 38
	v_writelane_b32 v255, s99, 39
	s_lshl_b32 s83, s1, 1
	s_lshl_b32 s1, s6, 9
	s_and_b32 s1, s1, 0x600
	v_and_b32_e32 v3, 63, v2
	v_bfe_u32 v4, v2, 5, 1
	s_add_u32 s6, s26, s2
	s_addc_u32 s7, s27, s3
	v_lshlrev_b32_e32 v0, 4, v4
	v_mov_b32_e32 v1, v155
	v_lshlrev_b32_e32 v5, 4, v3
	s_waitcnt vmcnt(17)
	v_lshl_add_u64 v[112:113], s[6:7], 0, v[0:1]
	v_bfe_u32 v125, v2, 3, 3
	v_and_b32_e32 v147, 7, v3
	v_bfe_u32 v146, v3, 4, 2
	v_xor_b32_e32 v146, v146, v147
	v_lshlrev_b32_e32 v146, 4, v146
	v_lshlrev_b32_e32 v147, 4, v147
	v_and_b32_e32 v0, 0x70, v5
	v_lshl_add_u64 v[114:115], s[4:5], 0, v[0:1]
	v_or_b32_e32 v1, 8, v125
	v_or_b32_e32 v6, 24, v125
	v_lshrrev_b32_e32 v9, 1, v1
	v_lshrrev_b32_e32 v10, 1, v6
	v_and_b32_e32 v124, 31, v2
	v_xor_b32_e32 v9, v9, v2
	v_xor_b32_e32 v10, v10, v2
	v_lshrrev_b32_e32 v11, 1, v2
	v_bfe_u32 v12, v2, 1, 3
	v_lshlrev_b32_e32 v13, 7, v2
	v_lshrrev_b32_e32 v16, 2, v2
	v_and_b32_e32 v17, 16, v2
	v_lshlrev_b32_e32 v2, 2, v2
	v_writelane_b32 v255, s1, 37
	s_movk_i32 s1, 0x70
	v_and_b32_e32 v18, 4, v125
	v_and_or_b32 v2, v2, 12, v17
	v_bitop3_b32 v8, v5, s1, v3 bitop3:0x48
	v_and_b32_e32 v5, 0x380, v5
	v_and_b32_e32 v13, 0xf80, v13
	v_and_or_b32 v16, v16, 3, v18
	v_lshlrev_b32_e32 v17, 1, v2
	v_or_b32_e32 v2, 1, v18
	v_lshl_add_u32 v7, v125, 7, s8
	v_lshl_add_u32 v1, v1, 7, s8
	v_lshl_add_u32 v6, v6, 7, s8
	v_add_u32_e32 v5, s8, v5
	v_add_u32_e32 v13, s8, v13
	v_lshl_add_u32 v16, v16, 7, s8
	v_cmp_ge_u32_e64 s[8:9], v2, v124
	v_or_b32_e32 v2, 2, v18
	v_cmp_ge_u32_e64 s[12:13], v2, v124
	v_cmp_le_u32_e64 s[14:15], v2, v124
	v_or_b32_e32 v2, 3, v125
	v_cmp_ge_u32_e64 s[16:17], v2, v124
	v_cmp_le_u32_e64 s[18:19], v2, v124
	v_or_b32_e32 v2, 8, v18
	v_cmp_ge_u32_e64 s[20:21], v2, v124
	v_cmp_le_u32_e64 s[22:23], v2, v124
	v_or_b32_e32 v2, 9, v18
	v_cmp_ge_u32_e64 s[24:25], v2, v124
	v_cmp_le_u32_e64 s[26:27], v2, v124
	v_or_b32_e32 v2, 10, v18
	v_cmp_ge_u32_e64 s[28:29], v2, v124
	v_cmp_le_u32_e64 s[30:31], v2, v124
	v_or_b32_e32 v2, 11, v125
	v_cmp_ge_u32_e64 s[34:35], v2, v124
	v_cmp_le_u32_e64 s[36:37], v2, v124
	v_or_b32_e32 v2, 16, v18
	v_cmp_ge_u32_e64 s[38:39], v2, v124
	v_cmp_le_u32_e64 s[40:41], v2, v124
	v_or_b32_e32 v2, 17, v18
	v_cmp_ge_u32_e64 s[42:43], v2, v124
	v_cmp_le_u32_e64 s[44:45], v2, v124
	v_or_b32_e32 v2, 18, v18
	v_readlane_b32 s1, v255, 27
	v_cmp_ge_u32_e64 s[46:47], v2, v124
	v_cmp_le_u32_e64 s[48:49], v2, v124
	v_or_b32_e32 v2, 19, v125
	s_add_u32 s94, s1, s2
	v_readlane_b32 s1, v255, 28
	v_cmp_ge_u32_e64 s[50:51], v2, v124
	v_cmp_le_u32_e64 s[52:53], v2, v124
	v_or_b32_e32 v2, 24, v18
	s_addc_u32 s95, s1, s3
	v_readlane_b32 s1, v255, 31
	v_cmp_ge_u32_e64 s[54:55], v2, v124
	v_cmp_le_u32_e64 s[56:57], v2, v124
	v_or_b32_e32 v2, 25, v18
	s_add_u32 s2, s1, s2
	v_readlane_b32 s1, v255, 32
	v_cmp_ge_u32_e64 s[58:59], v2, v124
	v_cmp_le_u32_e64 s[60:61], v2, v124
	v_or_b32_e32 v2, 26, v18
	s_addc_u32 s3, s1, s3
	s_ashr_i32 s1, s0, 31
	v_lshlrev_b32_e32 v9, 4, v9
	v_lshlrev_b32_e32 v10, 4, v10
	v_bitop3_b32 v11, v4, v11, 7 bitop3:0x78
	v_bitop3_b32 v14, v4, v12, 2 bitop3:0x36
	v_bitop3_b32 v15, v4, v12, 4 bitop3:0x36
	v_bitop3_b32 v12, v4, v12, 6 bitop3:0x36
	v_cmp_ge_u32_e64 s[62:63], v2, v124
	v_cmp_le_u32_e64 s[64:65], v2, v124
	v_or_b32_e32 v2, 27, v125
	s_lshl_b64 s[0:1], s[0:1], 2
	v_readlane_b32 s33, v255, 29
	v_lshlrev_b32_e32 v154, 3, v4
	v_and_b32_e32 v9, 0x70, v9
	v_and_b32_e32 v10, 0x70, v10
	v_lshlrev_b32_e32 v11, 4, v11
	v_lshlrev_b32_e32 v14, 4, v14
	v_lshlrev_b32_e32 v15, 4, v15
	v_lshlrev_b32_e32 v12, 4, v12
	v_cmp_ge_u32_e64 s[66:67], v2, v124
	v_cmp_le_u32_e64 s[68:69], v2, v124
	v_lshlrev_b32_e32 v2, 2, v4
	s_add_u32 s88, s33, s0
	v_readlane_b32 s0, v255, 30
	v_cmp_ge_u32_e64 s[4:5], v18, v124
	v_cmp_le_u32_e64 s[6:7], v18, v124
	v_cmp_lt_u32_e64 s[10:11], v18, v124
	s_waitcnt vmcnt(16)
	v_lshl_add_u64 v[116:117], s[94:95], 0, v[154:155]
	s_addc_u32 s89, s0, s1
	v_cmp_gt_u32_e64 s[70:71], 32, v3
	v_lshl_add_u64 v[118:119], s[2:3], 0, v[154:155]
	v_add_u32_e32 v126, v7, v8
	v_add_u32_e32 v127, v1, v9
	v_add_u32_e32 v128, v6, v10
	v_add_u32_e32 v129, v5, v0
	v_add_u32_e32 v130, v13, v11
	v_add_u32_e32 v131, v13, v14
	v_add_u32_e32 v132, v13, v15
	v_add_u32_e32 v133, v13, v12
	v_add_u32_e32 v134, v16, v17
	v_lshlrev_b32_e32 v154, 1, v2
	v_and_b32_e32 v192, 7, v124
	v_lshlrev_b32_e32 v192, 4, v192
	v_lshl_or_b32 v192, v124, 7, v192
	v_or_b32_e32 v192, v192, v154
	v_lshlrev_b32_e32 v194, 4, v125
	v_xor_b32_e32 v194, v194, v147
	v_lshl_add_u32 v193, v125, 7, v194
	s_mov_b32 s82, 0
	s_branch .LBB0_263

; __device__ __forceinline__ void attnA_unit(const Args& a, int unit, LAS unsigned char* lds) {
;     ...
;         for (int e = 0; e < 2; ++e) {
;             const int qt = 2 * wid + e, r = qt % dl, i0 = (512 * blk) / dl + 32 * (qt / dl);
;             const int tq = dl * (i0 + ql) + r;
;             bf16x8 qf[4];
;             { const bf16_t* qp = P + ((size_t)b * SEQ + tq) * PW + 64 * hh + 8 * h;
; #pragma unroll
;               for (int s = 0; s < 4; ++s) qf[s] = *(const bf16x8*)(qp + 16 * s); }
;             f32x16 o0, o1;
; #pragma unroll
;             for (int i = 0; i < 16; ++i) { o0[i] = 0.f; o1[i] = 0.f; }
;             float m = -1e30f, l = 0.f;
;             int kt0 = 0, kt1 = 4;
;             if (i0 - 64 < 0) kt0 = (i0 - 32 < 0) ? 2 : 1;
;             if (i0 + 64 >= Ls) kt1 = (i0 + 32 >= Ls) ? 2 : 3;
;             const unsigned pitch = (unsigned)dl * (PW * 2);
;             u32x4 pk[4], pv[4];
;             { const size_t ro = (size_t)(dl * (i0 - 64 + 32 * kt0) + r) * (PW * 2); gload32(pk, kbase + ro, pitch, lane); gload32(pv, vbase + ro, pitch, lane); }
.LaT_pass:
	s_or_b32 s0, s83, 0
	s_add_i32 s1, s72, -1
	s_and_b32 s74, s0, s1
	s_lshr_b32 s0, s0, s73
	s_lshl_b32 s0, s0, 5
	s_add_i32 s0, s0, s96
	v_add_u32_e32 v122, s0, v124
	v_lshlrev_b32_e32 v122, s73, v122
	v_add_u32_e32 v122, s74, v122
	v_add_u32_e32 v122, s76, v122
	v_mov_b32_e32 v123, 0
	v_add_u32_e32 v142, s0, v125
	v_lshlrev_b32_e32 v142, s73, v142
	v_add_u32_e32 v142, s74, v142
	v_add_u32_e32 v142, s76, v142
	s_movk_i32 s1, 0x1400
	v_mad_u64_u32 v[156:157], s[98:99], v122, s1, v[112:113]
	global_load_dwordx4 v[48:51], v[156:157], off
	global_load_dwordx4 v[52:55], v[156:157], off offset:32
	global_load_dwordx4 v[56:59], v[156:157], off offset:64
	global_load_dwordx4 v[60:63], v[156:157], off offset:96
	s_cmp_lt_i32 s0, 32
	s_cselect_b32 s1, 2, 1
	s_cmp_lt_i32 s0, 64
	s_cselect_b32 s86, s1, 0
	s_cmp_lt_i32 s0, s33
	s_cselect_b32 s1, 3, 2
	s_cmp_ge_i32 s0, s97
	s_cselect_b32 s87, s1, 4
	s_lshl_b32 s1, s86, 5
	s_add_i32 s0, s0, s1
	s_sub_i32 s75, s0, 64
	s_lshl_b32 s0, s75, s73
	s_add_i32 s0, s0, s74
	s_lshl_b32 s32, s83, 13
	s_mul_i32 s1, s0, 0x1400
	v_readlane_b32 s98, v255, 38
	v_readlane_b32 s99, v255, 39
	s_add_u32 s98, s98, s1
	s_addc_u32 s99, s99, 0
	s_sub_i32 s1, s92, 0x400
	s_mov_b32 m0, s32
	s_nop 0
	global_load_lds_dwordx4 v143, s[98:99]
	s_add_u32 s98, s98, s1
	s_addc_u32 s99, s99, 0
	global_load_lds_dwordx4 v144, s[98:99] offset:1024
	s_add_u32 s98, s98, s1
	s_addc_u32 s99, s99, 0
	global_load_lds_dwordx4 v143, s[98:99] offset:2048
	s_add_u32 s98, s98, s1
	s_addc_u32 s99, s99, 0
	global_load_lds_dwordx4 v144, s[98:99] offset:3072
	s_add_u32 s98, s98, 0x300
	s_addc_u32 s99, s99, 0
	s_add_i32 m0, s32, 0x1000
	s_nop 0
	global_load_lds_dwordx4 v145, s[98:99] offset:3072
	s_sub_u32 s98, s98, s1
	s_subb_u32 s99, s99, 0
	global_load_lds_dwordx4 v145, s[98:99] offset:2048
	s_sub_u32 s98, s98, s1
	s_subb_u32 s99, s99, 0
	global_load_lds_dwordx4 v145, s[98:99] offset:1024
	s_sub_u32 s98, s98, s1
	s_subb_u32 s99, s99, 0
	global_load_lds_dwordx4 v145, s[98:99]
	s_xor_b32 s32, s32, 0x2000
	s_add_i32 s75, s75, 32
	v_mov_b32_e32 v137, 0xf149f2ca
	v_mov_b32_e32 v135, 0
	v_mov_b32_e32 v16, 0
	v_mov_b32_e32 v17, 0
	v_mov_b32_e32 v18, 0
	v_mov_b32_e32 v19, 0
	v_mov_b32_e32 v20, 0
	v_mov_b32_e32 v21, 0
	v_mov_b32_e32 v22, 0
	v_mov_b32_e32 v23, 0
	v_mov_b32_e32 v24, 0
	v_mov_b32_e32 v25, 0
	v_mov_b32_e32 v26, 0
	v_mov_b32_e32 v27, 0
	v_mov_b32_e32 v28, 0
	v_mov_b32_e32 v29, 0
	v_mov_b32_e32 v30, 0
	v_mov_b32_e32 v31, 0
	v_mov_b32_e32 v0, 0
	v_mov_b32_e32 v1, 0
	v_mov_b32_e32 v2, 0
	v_mov_b32_e32 v3, 0
	v_mov_b32_e32 v4, 0
	v_mov_b32_e32 v5, 0
	v_mov_b32_e32 v6, 0
	v_mov_b32_e32 v7, 0
	v_mov_b32_e32 v8, 0
	v_mov_b32_e32 v9, 0
	v_mov_b32_e32 v10, 0
	v_mov_b32_e32 v11, 0
	v_mov_b32_e32 v12, 0
	v_mov_b32_e32 v13, 0
	v_mov_b32_e32 v14, 0
	v_mov_b32_e32 v15, 0
	s_or_b32 s0, s83, 1
	s_add_i32 s1, s72, -1
	s_and_b32 s81, s0, s1
	s_lshr_b32 s0, s0, s73
	s_lshl_b32 s0, s0, 5
	s_add_i32 s0, s0, s96
	v_add_u32_e32 v216, s0, v124
	v_lshlrev_b32_e32 v216, s73, v216
	v_add_u32_e32 v216, s81, v216
	v_add_u32_e32 v216, s76, v216
	v_mov_b32_e32 v217, 0
	v_add_u32_e32 v224, s0, v125
	v_lshlrev_b32_e32 v224, s73, v224
	v_add_u32_e32 v224, s81, v224
	v_add_u32_e32 v224, s76, v224
	s_movk_i32 s1, 0x1400
	v_mad_u64_u32 v[156:157], s[98:99], v216, s1, v[112:113]
	global_load_dwordx4 v[196:199], v[156:157], off
	global_load_dwordx4 v[200:203], v[156:157], off offset:32
	global_load_dwordx4 v[204:207], v[156:157], off offset:64
	global_load_dwordx4 v[208:211], v[156:157], off offset:96
	s_cmp_lt_i32 s0, 32
	s_cselect_b32 s1, 2, 1
	s_cmp_lt_i32 s0, 64
	s_cselect_b32 s2, s1, 0
	s_cmp_lt_i32 s0, s33
	s_cselect_b32 s1, 3, 2
	s_cmp_ge_i32 s0, s97
	s_cselect_b32 s3, s1, 4
	s_lshl_b32 s1, s2, 5
	s_add_i32 s0, s0, s1
	s_sub_i32 s80, s0, 64
	s_lshl_b32 s0, s80, s73
	s_add_i32 s0, s0, s81
	s_lshl_b32 s32, s83, 13
	s_add_i32 s32, s32, 0x2000
	s_mul_i32 s1, s0, 0x1400
	v_readlane_b32 s98, v255, 38
	v_readlane_b32 s99, v255, 39
	s_add_u32 s98, s98, s1
	s_addc_u32 s99, s99, 0
	s_sub_i32 s1, s92, 0x400
	s_mov_b32 m0, s32
	s_nop 0
	global_load_lds_dwordx4 v143, s[98:99]
	s_add_u32 s98, s98, s1
	s_addc_u32 s99, s99, 0
	global_load_lds_dwordx4 v144, s[98:99] offset:1024
	s_add_u32 s98, s98, s1
	s_addc_u32 s99, s99, 0
	global_load_lds_dwordx4 v143, s[98:99] offset:2048
	s_add_u32 s98, s98, s1
	s_addc_u32 s99, s99, 0
	global_load_lds_dwordx4 v144, s[98:99] offset:3072
	s_add_u32 s98, s98, 0x300
	s_addc_u32 s99, s99, 0
	s_add_i32 m0, s32, 0x1000
	s_nop 0
	global_load_lds_dwordx4 v145, s[98:99] offset:3072
	s_sub_u32 s98, s98, s1
	s_subb_u32 s99, s99, 0
	global_load_lds_dwordx4 v145, s[98:99] offset:2048
	s_sub_u32 s98, s98, s1
	s_subb_u32 s99, s99, 0
	global_load_lds_dwordx4 v145, s[98:99] offset:1024
	s_sub_u32 s98, s98, s1
	s_subb_u32 s99, s99, 0
	global_load_lds_dwordx4 v145, s[98:99]
	s_xor_b32 s32, s32, 0x2000
	s_add_i32 s80, s80, 32
	v_mov_b32_e32 v212, 0xf149f2ca
	v_mov_b32_e32 v213, 0
	v_mov_b32_e32 v80, 0
	v_mov_b32_e32 v81, 0
	v_mov_b32_e32 v82, 0
	v_mov_b32_e32 v83, 0
	v_mov_b32_e32 v84, 0
	v_mov_b32_e32 v85, 0
	v_mov_b32_e32 v86, 0
	v_mov_b32_e32 v87, 0
	v_mov_b32_e32 v88, 0
	v_mov_b32_e32 v89, 0
	v_mov_b32_e32 v90, 0
	v_mov_b32_e32 v91, 0
	v_mov_b32_e32 v92, 0
	v_mov_b32_e32 v93, 0
	v_mov_b32_e32 v94, 0
	v_mov_b32_e32 v95, 0
	v_mov_b32_e32 v64, 0
	v_mov_b32_e32 v65, 0
	v_mov_b32_e32 v66, 0
	v_mov_b32_e32 v67, 0
	v_mov_b32_e32 v68, 0
	v_mov_b32_e32 v69, 0
	v_mov_b32_e32 v70, 0
	v_mov_b32_e32 v71, 0
	v_mov_b32_e32 v72, 0
	v_mov_b32_e32 v73, 0
	v_mov_b32_e32 v74, 0
	v_mov_b32_e32 v75, 0
	v_mov_b32_e32 v76, 0
	v_mov_b32_e32 v77, 0
	v_mov_b32_e32 v78, 0
	v_mov_b32_e32 v79, 0
; #define LAS __attribute__((address_space(3)))
; template <bool KLDS>
; __device__ __forceinline__ void attn_step(const bf16x8 (&kf)[4], LAS const unsigned char* kb, const bf16x8 (&vf)[2][2], const bf16x8 (&qf)[4], f32x16& o0, f32x16& o1, float& m, float& l, int lane, int maskmode) {
;     ...
; #pragma unroll
;     for (int s = 0; s < 4; ++s) {
;         if (KLDS) { const int pc = (2 * s + h) ^ ((ql >> 1) & 7); const bf16x8 k1 = *(const LAS bf16x8*)(kb + ql * 128 + pc * 16); S = __builtin_amdgcn_mfma_f32_32x32x16_bf16(k1, qf[s], S, 0, 0, 0); }
;         else S = __builtin_amdgcn_mfma_f32_32x32x16_bf16(kf[s], qf[s], S, 0, 0, 0);
;     }
;     if (maskmode) {
; #pragma unroll
;         for (int i = 0; i < 16; ++i) { const int kr = (i & 3) + 8 * (i >> 2) + 4 * h; const bool ok = (maskmode == 1) ? (kr >= ql) : (kr <= ql); S[i] = ok ? S[i] : -1e30f; }
;     }
; __device__ __forceinline__ void attnA_unit(const Args& a, int unit, LAS unsigned char* lds) {
;     ...
;             for (int kt = kt0; kt <= kt1; ++kt) {
;                 asm volatile("" ::: "memory");
;                 lwrite32<true>(wl, pk, lane); lwrite32<false>(wl + 4096, pv, lane);
;                 if (kt < kt1) { const size_t ro = (size_t)(dl * (i0 - 64 + 32 * (kt + 1)) + r) * (PW * 2); gload32(pk, kbase + ro, pitch, lane); gload32(pv, vbase + ro, pitch, lane); }
;                 asm volatile("s_waitcnt lgkmcnt(0)" ::: "memory");
;                 bf16x8 kf[4], vf[2][2];
;                 load_kf(wl, kf, lane); load_vf(wl + 4096, vf, lane);
;                 attn_step<false>(kf, wl, vf, qf, o0, o1, m, l, lane, kt == 0 ? 1 : (kt == 4 ? 2 : 0));
.LaT_loop:
	s_waitcnt vmcnt(0)
	ds_read_b128 v[160:163], v130
	ds_read_b128 v[164:167], v131
	ds_read_b128 v[168:171], v132
	ds_read_b128 v[172:175], v133
	ds_read_b128 v[176:179], v130 offset:8192
	ds_read_b128 v[180:183], v131 offset:8192
	ds_read_b128 v[184:187], v132 offset:8192
	ds_read_b128 v[188:191], v133 offset:8192
	s_waitcnt lgkmcnt(7)
	v_mfma_f32_32x32x16_bf16 v[32:47], v[160:163], v[48:51], 0
	s_waitcnt lgkmcnt(3)
	v_mfma_f32_32x32x16_bf16 v[96:111], v[176:179], v[196:199], 0
	s_waitcnt lgkmcnt(6)
	v_mfma_f32_32x32x16_bf16 v[32:47], v[164:167], v[52:55], v[32:47]
	s_waitcnt lgkmcnt(2)
	v_mfma_f32_32x32x16_bf16 v[96:111], v[180:183], v[200:203], v[96:111]
	s_waitcnt lgkmcnt(5)
	v_mfma_f32_32x32x16_bf16 v[32:47], v[168:171], v[56:59], v[32:47]
	s_waitcnt lgkmcnt(1)
	v_mfma_f32_32x32x16_bf16 v[96:111], v[184:187], v[204:207], v[96:111]
	s_waitcnt lgkmcnt(4)
	v_mfma_f32_32x32x16_bf16 v[32:47], v[172:175], v[60:63], v[32:47]
	s_waitcnt lgkmcnt(0)
	v_mfma_f32_32x32x16_bf16 v[96:111], v[188:191], v[208:211], v[96:111]
	ds_read_b64_tr_b16 v[160:161], v134 offset:4096
	ds_read_b64_tr_b16 v[162:163], v134 offset:5120
	ds_read_b64_tr_b16 v[164:165], v134 offset:4160
	ds_read_b64_tr_b16 v[166:167], v134 offset:5184
	ds_read_b64_tr_b16 v[168:169], v134 offset:6144
	ds_read_b64_tr_b16 v[170:171], v134 offset:7168
	ds_read_b64_tr_b16 v[172:173], v134 offset:6208
	ds_read_b64_tr_b16 v[174:175], v134 offset:7232
	ds_read_b64_tr_b16 v[176:177], v134 offset:12288
	ds_read_b64_tr_b16 v[178:179], v134 offset:13312
	ds_read_b64_tr_b16 v[180:181], v134 offset:12352
	ds_read_b64_tr_b16 v[182:183], v134 offset:13376
	ds_read_b64_tr_b16 v[184:185], v134 offset:14336
	ds_read_b64_tr_b16 v[186:187], v134 offset:15360
	ds_read_b64_tr_b16 v[188:189], v134 offset:14400
	ds_read_b64_tr_b16 v[190:191], v134 offset:15424
	s_nop 7
	s_cmp_gt_u32 s86, s87
	s_cbranch_scc1 .LaT_m3a
	s_cmp_eq_u32 s86, 0
	s_cbranch_scc1 .LaT_m1a
	s_cmp_eq_u32 s86, 4
	s_cbranch_scc0 .LaT_m0a
	v_cndmask_b32_e64 v32, v237, v32, s[6:7]
	v_cndmask_b32_e64 v33, v237, v33, s[10:11]
	v_cndmask_b32_e64 v34, v237, v34, s[14:15]
	v_cndmask_b32_e64 v35, v237, v35, s[18:19]
	v_cndmask_b32_e64 v36, v237, v36, s[22:23]
	v_cndmask_b32_e64 v37, v237, v37, s[26:27]
	v_cndmask_b32_e64 v38, v237, v38, s[30:31]
	v_cndmask_b32_e64 v39, v237, v39, s[36:37]
	v_cndmask_b32_e64 v40, v237, v40, s[40:41]
	v_cndmask_b32_e64 v41, v237, v41, s[44:45]
	v_cndmask_b32_e64 v42, v237, v42, s[48:49]
	v_cndmask_b32_e64 v43, v237, v43, s[52:53]
	v_cndmask_b32_e64 v44, v237, v44, s[56:57]
	v_cndmask_b32_e64 v45, v237, v45, s[60:61]
	v_cndmask_b32_e64 v46, v237, v46, s[64:65]
	v_cndmask_b32_e64 v47, v237, v47, s[68:69]
	s_branch .LaT_m0a
.LaT_m1a:
	v_cndmask_b32_e64 v32, v237, v32, s[4:5]
	v_cndmask_b32_e64 v33, v237, v33, s[8:9]
	v_cndmask_b32_e64 v34, v237, v34, s[12:13]
	v_cndmask_b32_e64 v35, v237, v35, s[16:17]
	v_cndmask_b32_e64 v36, v237, v36, s[20:21]
	v_cndmask_b32_e64 v37, v237, v37, s[24:25]
	v_cndmask_b32_e64 v38, v237, v38, s[28:29]
	v_cndmask_b32_e64 v39, v237, v39, s[34:35]
	v_cndmask_b32_e64 v40, v237, v40, s[38:39]
	v_cndmask_b32_e64 v41, v237, v41, s[42:43]
	v_cndmask_b32_e64 v42, v237, v42, s[46:47]
	v_cndmask_b32_e64 v43, v237, v43, s[50:51]
	v_cndmask_b32_e64 v44, v237, v44, s[54:55]
	v_cndmask_b32_e64 v45, v237, v45, s[58:59]
	v_cndmask_b32_e64 v46, v237, v46, s[62:63]
	v_cndmask_b32_e64 v47, v237, v47, s[66:67]
	s_branch .LaT_m0a
.LaT_m3a:
	v_mov_b32_e32 v32, v237
	v_mov_b32_e32 v33, v237
	v_mov_b32_e32 v34, v237
	v_mov_b32_e32 v35, v237
	v_mov_b32_e32 v36, v237
	v_mov_b32_e32 v37, v237
	v_mov_b32_e32 v38, v237
	v_mov_b32_e32 v39, v237
	v_mov_b32_e32 v40, v237
	v_mov_b32_e32 v41, v237
	v_mov_b32_e32 v42, v237
	v_mov_b32_e32 v43, v237
	v_mov_b32_e32 v44, v237
	v_mov_b32_e32 v45, v237
	v_mov_b32_e32 v46, v237
	v_mov_b32_e32 v47, v237
.LaT_m0a:
	s_cmp_gt_u32 s2, s3
	s_cbranch_scc1 .LaT_m3b
	s_cmp_eq_u32 s2, 0
	s_cbranch_scc1 .LaT_m1b
	s_cmp_eq_u32 s2, 4
	s_cbranch_scc0 .LaT_m0b
	v_cndmask_b32_e64 v96, v237, v96, s[6:7]
	v_cndmask_b32_e64 v97, v237, v97, s[10:11]
	v_cndmask_b32_e64 v98, v237, v98, s[14:15]
	v_cndmask_b32_e64 v99, v237, v99, s[18:19]
	v_cndmask_b32_e64 v100, v237, v100, s[22:23]
	v_cndmask_b32_e64 v101, v237, v101, s[26:27]
	v_cndmask_b32_e64 v102, v237, v102, s[30:31]
	v_cndmask_b32_e64 v103, v237, v103, s[36:37]
	v_cndmask_b32_e64 v104, v237, v104, s[40:41]
	v_cndmask_b32_e64 v105, v237, v105, s[44:45]
	v_cndmask_b32_e64 v106, v237, v106, s[48:49]
	v_cndmask_b32_e64 v107, v237, v107, s[52:53]
	v_cndmask_b32_e64 v108, v237, v108, s[56:57]
	v_cndmask_b32_e64 v109, v237, v109, s[60:61]
	v_cndmask_b32_e64 v110, v237, v110, s[64:65]
	v_cndmask_b32_e64 v111, v237, v111, s[68:69]
	s_branch .LaT_m0b
.LaT_m1b:
	v_cndmask_b32_e64 v96, v237, v96, s[4:5]
	v_cndmask_b32_e64 v97, v237, v97, s[8:9]
	v_cndmask_b32_e64 v98, v237, v98, s[12:13]
	v_cndmask_b32_e64 v99, v237, v99, s[16:17]
	v_cndmask_b32_e64 v100, v237, v100, s[20:21]
	v_cndmask_b32_e64 v101, v237, v101, s[24:25]
	v_cndmask_b32_e64 v102, v237, v102, s[28:29]
	v_cndmask_b32_e64 v103, v237, v103, s[34:35]
	v_cndmask_b32_e64 v104, v237, v104, s[38:39]
	v_cndmask_b32_e64 v105, v237, v105, s[42:43]
	v_cndmask_b32_e64 v106, v237, v106, s[46:47]
	v_cndmask_b32_e64 v107, v237, v107, s[50:51]
	v_cndmask_b32_e64 v108, v237, v108, s[54:55]
	v_cndmask_b32_e64 v109, v237, v109, s[58:59]
	v_cndmask_b32_e64 v110, v237, v110, s[62:63]
	v_cndmask_b32_e64 v111, v237, v111, s[66:67]
	s_branch .LaT_m0b
; __device__ __forceinline__ float fexp2(float x) { return __builtin_amdgcn_exp2f(x); }
; template <bool KLDS>
; __device__ __forceinline__ void attn_step(const bf16x8 (&kf)[4], LAS const unsigned char* kb, const bf16x8 (&vf)[2][2], const bf16x8 (&qf)[4], f32x16& o0, f32x16& o1, float& m, float& l, int lane, int maskmode) {
;     ...
;     float tm = S[0];
; #pragma unroll
;     for (int i = 1; i < 16; ++i) tm = fmaxf(tm, S[i]);
;     tm = fmaxf(tm, __shfl_xor(tm, 32));
;     const float mn = fmaxf(m, tm), al = fexp2(m - mn); m = mn;
;     float ps = 0.f;
; #pragma unroll
;     for (int i = 0; i < 16; ++i) { S[i] = fexp2(S[i] - mn); ps += S[i]; }
;     l = l * al + ps;
; __device__ __forceinline__ void attnA_unit(const Args& a, int unit, LAS unsigned char* lds) {
;     ...
;                 if (kt < kt1) { const size_t ro = (size_t)(dl * (i0 - 64 + 32 * (kt + 1)) + r) * (PW * 2); gload32(pk, kbase + ro, pitch, lane); gload32(pv, vbase + ro, pitch, lane); }
.LaT_m3b:
	v_mov_b32_e32 v96, v237
	v_mov_b32_e32 v97, v237
	v_mov_b32_e32 v98, v237
	v_mov_b32_e32 v99, v237
	v_mov_b32_e32 v100, v237
	v_mov_b32_e32 v101, v237
	v_mov_b32_e32 v102, v237
	v_mov_b32_e32 v103, v237
	v_mov_b32_e32 v104, v237
	v_mov_b32_e32 v105, v237
	v_mov_b32_e32 v106, v237
	v_mov_b32_e32 v107, v237
	v_mov_b32_e32 v108, v237
	v_mov_b32_e32 v109, v237
	v_mov_b32_e32 v110, v237
	v_mov_b32_e32 v111, v237
.LaT_m0b:
	s_waitcnt lgkmcnt(0)
	s_cmp_lt_u32 s86, s87
	s_cbranch_scc0 .LaT_nda
	s_lshl_b32 s0, s75, s73
	s_add_i32 s0, s0, s74
	s_lshl_b32 s32, s83, 13
	s_mul_i32 s1, s0, 0x1400
	v_readlane_b32 s98, v255, 38
	v_readlane_b32 s99, v255, 39
	s_add_u32 s98, s98, s1
	s_addc_u32 s99, s99, 0
	s_sub_i32 s1, s92, 0x400
	s_mov_b32 m0, s32
	s_nop 0
	global_load_lds_dwordx4 v143, s[98:99]
	s_add_u32 s98, s98, s1
	s_addc_u32 s99, s99, 0
	global_load_lds_dwordx4 v144, s[98:99] offset:1024
	s_add_u32 s98, s98, s1
	s_addc_u32 s99, s99, 0
	global_load_lds_dwordx4 v143, s[98:99] offset:2048
	s_add_u32 s98, s98, s1
	s_addc_u32 s99, s99, 0
	global_load_lds_dwordx4 v144, s[98:99] offset:3072
	s_add_u32 s98, s98, 0x300
	s_addc_u32 s99, s99, 0
	s_add_i32 m0, s32, 0x1000
	s_nop 0
	global_load_lds_dwordx4 v145, s[98:99] offset:3072
	s_sub_u32 s98, s98, s1
	s_subb_u32 s99, s99, 0
	global_load_lds_dwordx4 v145, s[98:99] offset:2048
	s_sub_u32 s98, s98, s1
	s_subb_u32 s99, s99, 0
	global_load_lds_dwordx4 v145, s[98:99] offset:1024
	s_sub_u32 s98, s98, s1
	s_subb_u32 s99, s99, 0
	global_load_lds_dwordx4 v145, s[98:99]
	s_xor_b32 s32, s32, 0x2000
.LaT_nda:
	s_add_i32 s75, s75, 32
	s_cmp_lt_u32 s2, s3
	s_cbranch_scc0 .LaT_ndb
	s_lshl_b32 s0, s80, s73
	s_add_i32 s0, s0, s81
	s_lshl_b32 s32, s83, 13
	s_add_i32 s32, s32, 0x2000
	s_mul_i32 s1, s0, 0x1400
	v_readlane_b32 s98, v255, 38
	v_readlane_b32 s99, v255, 39
	s_add_u32 s98, s98, s1
	s_addc_u32 s99, s99, 0
	s_sub_i32 s1, s92, 0x400
	s_mov_b32 m0, s32
	s_nop 0
	global_load_lds_dwordx4 v143, s[98:99]
	s_add_u32 s98, s98, s1
	s_addc_u32 s99, s99, 0
	global_load_lds_dwordx4 v144, s[98:99] offset:1024
	s_add_u32 s98, s98, s1
	s_addc_u32 s99, s99, 0
	global_load_lds_dwordx4 v143, s[98:99] offset:2048
	s_add_u32 s98, s98, s1
	s_addc_u32 s99, s99, 0
	global_load_lds_dwordx4 v144, s[98:99] offset:3072
	s_add_u32 s98, s98, 0x300
	s_addc_u32 s99, s99, 0
	s_add_i32 m0, s32, 0x1000
	s_nop 0
	global_load_lds_dwordx4 v145, s[98:99] offset:3072
	s_sub_u32 s98, s98, s1
	s_subb_u32 s99, s99, 0
	global_load_lds_dwordx4 v145, s[98:99] offset:2048
	s_sub_u32 s98, s98, s1
	s_subb_u32 s99, s99, 0
	global_load_lds_dwordx4 v145, s[98:99] offset:1024
	s_sub_u32 s98, s98, s1
	s_subb_u32 s99, s99, 0
	global_load_lds_dwordx4 v145, s[98:99]
	s_xor_b32 s32, s32, 0x2000
.LaT_ndb:
	s_add_i32 s80, s80, 32
	v_max3_f32 v138, v32, v33, v34
	v_max3_f32 v148, v96, v97, v98
	v_max3_f32 v138, v138, v35, v36
	v_max3_f32 v148, v148, v99, v100
	v_max3_f32 v138, v138, v37, v38
	v_max3_f32 v148, v148, v101, v102
	v_max3_f32 v138, v138, v39, v40
	v_max3_f32 v148, v148, v103, v104
	v_max3_f32 v138, v138, v41, v42
	v_max3_f32 v148, v148, v105, v106
	v_max3_f32 v138, v138, v43, v44
	v_max3_f32 v148, v148, v107, v108
	v_max3_f32 v138, v138, v45, v46
	v_max3_f32 v148, v148, v109, v110
	v_max_f32_e32 v138, v138, v47
	v_max_f32_e32 v148, v148, v111
	v_mov_b32_e32 v139, v138
	v_mov_b32_e32 v149, v148
	s_nop 1
	s_nop 1
	v_permlane32_swap_b32_e32 v139, v138
	v_permlane32_swap_b32_e32 v149, v148
	v_max3_f32 v138, v137, v138, v139
	v_max3_f32 v148, v212, v148, v149
	v_sub_f32_e32 v140, v137, v138
	v_sub_f32_e32 v150, v212, v148
	v_exp_f32_e32 v140, v140
	v_exp_f32_e32 v150, v150
	v_mov_b32_e32 v137, v138
	v_mov_b32_e32 v212, v148
	v_sub_f32_e32 v32, v32, v138
	v_sub_f32_e32 v96, v96, v148
	v_sub_f32_e32 v33, v33, v138
	v_sub_f32_e32 v97, v97, v148
	v_sub_f32_e32 v34, v34, v138
	v_sub_f32_e32 v98, v98, v148
	v_sub_f32_e32 v35, v35, v138
	v_sub_f32_e32 v99, v99, v148
	v_sub_f32_e32 v36, v36, v138
	v_sub_f32_e32 v100, v100, v148
	v_sub_f32_e32 v37, v37, v138
	v_sub_f32_e32 v101, v101, v148
	v_sub_f32_e32 v38, v38, v138
	v_sub_f32_e32 v102, v102, v148
	v_sub_f32_e32 v39, v39, v138
	v_sub_f32_e32 v103, v103, v148
	v_sub_f32_e32 v40, v40, v138
	v_sub_f32_e32 v104, v104, v148
	v_sub_f32_e32 v41, v41, v138
	v_sub_f32_e32 v105, v105, v148
	v_sub_f32_e32 v42, v42, v138
	v_sub_f32_e32 v106, v106, v148
	v_sub_f32_e32 v43, v43, v138
	v_sub_f32_e32 v107, v107, v148
	v_sub_f32_e32 v44, v44, v138
	v_sub_f32_e32 v108, v108, v148
	v_sub_f32_e32 v45, v45, v138
	v_sub_f32_e32 v109, v109, v148
	v_sub_f32_e32 v46, v46, v138
	v_sub_f32_e32 v110, v110, v148
	v_sub_f32_e32 v47, v47, v138
	v_sub_f32_e32 v111, v111, v148
	v_exp_f32_e32 v32, v32
	v_exp_f32_e32 v96, v96
	v_exp_f32_e32 v33, v33
	v_exp_f32_e32 v97, v97
	v_exp_f32_e32 v34, v34
	v_exp_f32_e32 v98, v98
	v_exp_f32_e32 v35, v35
	v_exp_f32_e32 v99, v99
	v_pk_add_f32 v[152:153], v[32:33], v[34:35]
	v_pk_add_f32 v[218:219], v[96:97], v[98:99]
	v_exp_f32_e32 v36, v36
	v_exp_f32_e32 v100, v100
	v_exp_f32_e32 v37, v37
	v_exp_f32_e32 v101, v101
	v_pk_add_f32 v[152:153], v[152:153], v[36:37]
	v_pk_add_f32 v[218:219], v[218:219], v[100:101]
	v_exp_f32_e32 v38, v38
	v_exp_f32_e32 v102, v102
	v_exp_f32_e32 v39, v39
	v_exp_f32_e32 v103, v103
	v_pk_add_f32 v[152:153], v[152:153], v[38:39]
	v_pk_add_f32 v[218:219], v[218:219], v[102:103]
	v_exp_f32_e32 v40, v40
	v_exp_f32_e32 v104, v104
	v_exp_f32_e32 v41, v41
	v_exp_f32_e32 v105, v105
	v_pk_add_f32 v[152:153], v[152:153], v[40:41]
	v_pk_add_f32 v[218:219], v[218:219], v[104:105]
	v_exp_f32_e32 v42, v42
	v_exp_f32_e32 v106, v106
	v_exp_f32_e32 v43, v43
	v_exp_f32_e32 v107, v107
; __device__ __forceinline__ unsigned pk2(float lo, float hi) { unsigned r; asm("v_cvt_pk_bf16_f32 %0, %1, %2" : "=v"(r) : "v"(lo), "v"(hi)); return r; }
; __device__ __forceinline__ unsigned pk2n(float lo, float hi) { const f32x2v v = {lo, hi}; const bf16v2 b = __builtin_convertvector(v, bf16v2); return __builtin_bit_cast(unsigned, b); }
; __device__ __forceinline__ float fexp2(float x) { return __builtin_amdgcn_exp2f(x); }
; template <bool KLDS>
; __device__ __forceinline__ void attn_step(const bf16x8 (&kf)[4], LAS const unsigned char* kb, const bf16x8 (&vf)[2][2], const bf16x8 (&qf)[4], f32x16& o0, f32x16& o1, float& m, float& l, int lane, int maskmode) {
;     ...
;     for (int i = 0; i < 16; ++i) { S[i] = fexp2(S[i] - mn); ps += S[i]; }
;     l = l * al + ps;
; #pragma unroll
;     for (int i = 0; i < 16; ++i) { o0[i] *= al; o1[i] *= al; }
;     bf16x8 pf[2];
; #pragma unroll
;     for (int s2 = 0; s2 < 2; ++s2) {
;         u32x4 w; w.x = pk2n(S[8 * s2 + 0], S[8 * s2 + 1]); w.y = pk2n(S[8 * s2 + 2], S[8 * s2 + 3]); w.z = pk2n(S[8 * s2 + 4], S[8 * s2 + 5]); w.w = pk2n(S[8 * s2 + 6], S[8 * s2 + 7]);
;         pf[s2] = __builtin_bit_cast(bf16x8, w);
;     }
; #pragma unroll
;     for (int s2 = 0; s2 < 2; ++s2) {
;         o0 = __builtin_amdgcn_mfma_f32_32x32x16_bf16(vf[s2][0], pf[s2], o0, 0, 0, 0);
;         o1 = __builtin_amdgcn_mfma_f32_32x32x16_bf16(vf[s2][1], pf[s2], o1, 0, 0, 0);
;     }
; __device__ __forceinline__ void attnA_unit(const Args& a, int unit, LAS unsigned char* lds) {
;     ...
;             const float lt = l + __shfl_xor(l, 32);
;             const float inv = 1.0f / lt, lse = m + __builtin_amdgcn_logf(lt);
;             const size_t tokg = (size_t)b * SEQ + tq;
;             if (pidx < 2) {
;                 bf16_t* op = OA + ((size_t)pidx * MTOK + tokg) * 384 + 64 * hh;
; #pragma unroll
;                 for (int dt = 0; dt < 2; ++dt)
; #pragma unroll
;                     for (int g = 0; g < 4; ++g) {
;                         const f32x16& o = dt ? o1 : o0;
;                         u32x2 w; w.x = pk2(o[4 * g] * inv, o[4 * g + 1] * inv); w.y = pk2(o[4 * g + 2] * inv, o[4 * g + 3] * inv);
;                         *(u32x2*)(op + 32 * dt + 8 * g + 4 * h) = w;
;                     }
;                 if (h == 0) LSE[((size_t)pidx * MTOK + tokg) * 6 + hh] = lse;
	v_pk_add_f32 v[152:153], v[152:153], v[42:43]
	v_pk_add_f32 v[218:219], v[218:219], v[106:107]
	v_exp_f32_e32 v44, v44
	v_exp_f32_e32 v108, v108
	v_exp_f32_e32 v45, v45
	v_exp_f32_e32 v109, v109
	v_pk_add_f32 v[152:153], v[152:153], v[44:45]
	v_pk_add_f32 v[218:219], v[218:219], v[108:109]
	v_exp_f32_e32 v46, v46
	v_exp_f32_e32 v110, v110
	v_exp_f32_e32 v47, v47
	v_exp_f32_e32 v111, v111
	v_pk_add_f32 v[152:153], v[152:153], v[46:47]
	v_pk_add_f32 v[218:219], v[218:219], v[110:111]
	s_nop 0
	s_nop 0
	v_add_f32_e32 v152, v152, v153
	v_add_f32_e32 v218, v218, v219
	v_fma_f32 v135, v135, v140, v152
	v_fma_f32 v213, v213, v150, v218
	v_pk_mul_f32 v[16:17], v[16:17], v[140:141] op_sel_hi:[1,0]
	v_pk_mul_f32 v[80:81], v[80:81], v[150:151] op_sel_hi:[1,0]
	v_pk_mul_f32 v[18:19], v[18:19], v[140:141] op_sel_hi:[1,0]
	v_pk_mul_f32 v[82:83], v[82:83], v[150:151] op_sel_hi:[1,0]
	v_pk_mul_f32 v[20:21], v[20:21], v[140:141] op_sel_hi:[1,0]
	v_pk_mul_f32 v[84:85], v[84:85], v[150:151] op_sel_hi:[1,0]
	v_pk_mul_f32 v[22:23], v[22:23], v[140:141] op_sel_hi:[1,0]
	v_pk_mul_f32 v[86:87], v[86:87], v[150:151] op_sel_hi:[1,0]
	v_pk_mul_f32 v[24:25], v[24:25], v[140:141] op_sel_hi:[1,0]
	v_pk_mul_f32 v[88:89], v[88:89], v[150:151] op_sel_hi:[1,0]
	v_pk_mul_f32 v[26:27], v[26:27], v[140:141] op_sel_hi:[1,0]
	v_pk_mul_f32 v[90:91], v[90:91], v[150:151] op_sel_hi:[1,0]
	v_pk_mul_f32 v[28:29], v[28:29], v[140:141] op_sel_hi:[1,0]
	v_pk_mul_f32 v[92:93], v[92:93], v[150:151] op_sel_hi:[1,0]
	v_pk_mul_f32 v[30:31], v[30:31], v[140:141] op_sel_hi:[1,0]
	v_pk_mul_f32 v[94:95], v[94:95], v[150:151] op_sel_hi:[1,0]
	v_pk_mul_f32 v[0:1], v[0:1], v[140:141] op_sel_hi:[1,0]
	v_pk_mul_f32 v[64:65], v[64:65], v[150:151] op_sel_hi:[1,0]
	v_pk_mul_f32 v[2:3], v[2:3], v[140:141] op_sel_hi:[1,0]
	v_pk_mul_f32 v[66:67], v[66:67], v[150:151] op_sel_hi:[1,0]
	v_pk_mul_f32 v[4:5], v[4:5], v[140:141] op_sel_hi:[1,0]
	v_pk_mul_f32 v[68:69], v[68:69], v[150:151] op_sel_hi:[1,0]
	v_pk_mul_f32 v[6:7], v[6:7], v[140:141] op_sel_hi:[1,0]
	v_pk_mul_f32 v[70:71], v[70:71], v[150:151] op_sel_hi:[1,0]
	v_pk_mul_f32 v[8:9], v[8:9], v[140:141] op_sel_hi:[1,0]
	v_pk_mul_f32 v[72:73], v[72:73], v[150:151] op_sel_hi:[1,0]
	v_pk_mul_f32 v[10:11], v[10:11], v[140:141] op_sel_hi:[1,0]
	v_pk_mul_f32 v[74:75], v[74:75], v[150:151] op_sel_hi:[1,0]
	v_pk_mul_f32 v[12:13], v[12:13], v[140:141] op_sel_hi:[1,0]
	v_pk_mul_f32 v[76:77], v[76:77], v[150:151] op_sel_hi:[1,0]
	v_pk_mul_f32 v[14:15], v[14:15], v[140:141] op_sel_hi:[1,0]
	v_pk_mul_f32 v[78:79], v[78:79], v[150:151] op_sel_hi:[1,0]
	v_cvt_pk_bf16_f32 v32, v32, v33
	v_cvt_pk_bf16_f32 v96, v96, v97
	v_cvt_pk_bf16_f32 v33, v34, v35
	v_cvt_pk_bf16_f32 v97, v98, v99
	v_cvt_pk_bf16_f32 v34, v36, v37
	v_cvt_pk_bf16_f32 v98, v100, v101
	v_cvt_pk_bf16_f32 v35, v38, v39
	v_cvt_pk_bf16_f32 v99, v102, v103
	v_cvt_pk_bf16_f32 v36, v40, v41
	v_cvt_pk_bf16_f32 v100, v104, v105
	v_cvt_pk_bf16_f32 v37, v42, v43
	v_cvt_pk_bf16_f32 v101, v106, v107
	v_cvt_pk_bf16_f32 v38, v44, v45
	v_cvt_pk_bf16_f32 v102, v108, v109
	v_cvt_pk_bf16_f32 v39, v46, v47
	v_cvt_pk_bf16_f32 v103, v110, v111
	s_nop 0
	v_mfma_f32_32x32x16_bf16 v[16:31], v[160:163], v[32:35], v[16:31]
	v_mfma_f32_32x32x16_bf16 v[80:95], v[176:179], v[96:99], v[80:95]
	v_mfma_f32_32x32x16_bf16 v[0:15], v[164:167], v[32:35], v[0:15]
	v_mfma_f32_32x32x16_bf16 v[64:79], v[180:183], v[96:99], v[64:79]
	v_mfma_f32_32x32x16_bf16 v[16:31], v[168:171], v[36:39], v[16:31]
	v_mfma_f32_32x32x16_bf16 v[80:95], v[184:187], v[100:103], v[80:95]
	v_mfma_f32_32x32x16_bf16 v[0:15], v[172:175], v[36:39], v[0:15]
	v_mfma_f32_32x32x16_bf16 v[64:79], v[188:191], v[100:103], v[64:79]
	s_add_i32 s86, s86, 1
	s_add_i32 s2, s2, 1
	s_cmp_le_u32 s86, s87
	s_cbranch_scc1 .LaT_loop
	s_cmp_le_u32 s2, s3
	s_cbranch_scc1 .LaT_loop
	s_nop 15
	s_nop 7
	s_lshl_b32 s32, s83, 13
	v_mov_b32_e32 v39, v135
	s_nop 1
	v_permlane32_swap_b32_e32 v39, v135
	v_add_f32_e32 v63, v135, v39
	v_add_u32_e32 v40, s32, v192
	v_log_f32_e32 v34, v63
	v_div_scale_f32 v35, s[0:1], v63, v63, 1.0
	v_rcp_f32_e32 v37, v35
	v_div_scale_f32 v38, vcc, 1.0, v63, 1.0
	v_fma_f32 v62, -v35, v37, 1.0
	v_fmac_f32_e32 v37, v62, v37
	v_mul_f32_e32 v62, v38, v37
	v_fma_f32 v33, -v35, v62, v38
	v_fmac_f32_e32 v62, v33, v37
	v_fma_f32 v35, -v35, v62, v38
	v_div_fmas_f32 v35, v35, v37, v62
	v_div_fixup_f32 v33, v35, v63, 1.0
	v_add_f32_e32 v36, v137, v34
	s_lshl_b32 s80, 8, s73
	s_and_b64 vcc, exec, s[90:91]
	s_cbranch_vccz .LaT_mga
	v_mul_f32_e32 v52, v16, v33
	v_mul_f32_e32 v53, v17, v33
	v_mul_f32_e32 v54, v18, v33
	v_mul_f32_e32 v55, v19, v33
	v_cvt_pk_bf16_f32 v48, v52, v53
	v_cvt_pk_bf16_f32 v49, v54, v55
	v_xor_b32_e32 v41, 0x0, v40
	ds_write_b64 v41, v[48:49]
	v_mul_f32_e32 v52, v20, v33
	v_mul_f32_e32 v53, v21, v33
	v_mul_f32_e32 v54, v22, v33
	v_mul_f32_e32 v55, v23, v33
	v_cvt_pk_bf16_f32 v50, v52, v53
	v_cvt_pk_bf16_f32 v51, v54, v55
	v_xor_b32_e32 v41, 0x10, v40
	ds_write_b64 v41, v[50:51]
	v_mul_f32_e32 v52, v24, v33
	v_mul_f32_e32 v53, v25, v33
	v_mul_f32_e32 v54, v26, v33
	v_mul_f32_e32 v55, v27, v33
	v_cvt_pk_bf16_f32 v48, v52, v53
	v_cvt_pk_bf16_f32 v49, v54, v55
	v_xor_b32_e32 v41, 0x20, v40
	ds_write_b64 v41, v[48:49]
	v_mul_f32_e32 v52, v28, v33
	v_mul_f32_e32 v53, v29, v33
	v_mul_f32_e32 v54, v30, v33
	v_mul_f32_e32 v55, v31, v33
	v_cvt_pk_bf16_f32 v50, v52, v53
	v_cvt_pk_bf16_f32 v51, v54, v55
	v_xor_b32_e32 v41, 0x30, v40
	ds_write_b64 v41, v[50:51]
	v_mul_f32_e32 v52, v0, v33
	v_mul_f32_e32 v53, v1, v33
	v_mul_f32_e32 v54, v2, v33
	v_mul_f32_e32 v55, v3, v33
	v_cvt_pk_bf16_f32 v48, v52, v53
	v_cvt_pk_bf16_f32 v49, v54, v55
	v_xor_b32_e32 v41, 0x40, v40
	ds_write_b64 v41, v[48:49]
	v_mul_f32_e32 v52, v4, v33
	v_mul_f32_e32 v53, v5, v33
	v_mul_f32_e32 v54, v6, v33
	v_mul_f32_e32 v55, v7, v33
	v_cvt_pk_bf16_f32 v50, v52, v53
	v_cvt_pk_bf16_f32 v51, v54, v55
	v_xor_b32_e32 v41, 0x50, v40
	ds_write_b64 v41, v[50:51]
	v_mul_f32_e32 v52, v8, v33
	v_mul_f32_e32 v53, v9, v33
	v_mul_f32_e32 v54, v10, v33
	v_mul_f32_e32 v55, v11, v33
	v_cvt_pk_bf16_f32 v48, v52, v53
	v_cvt_pk_bf16_f32 v49, v54, v55
	v_xor_b32_e32 v41, 0x60, v40
	ds_write_b64 v41, v[48:49]
	v_mul_f32_e32 v52, v12, v33
	v_mul_f32_e32 v53, v13, v33
	v_mul_f32_e32 v54, v14, v33
	v_mul_f32_e32 v55, v15, v33
	v_cvt_pk_bf16_f32 v50, v52, v53
	v_cvt_pk_bf16_f32 v51, v54, v55
	v_xor_b32_e32 v41, 0x70, v40
	ds_write_b64 v41, v[50:51]
	v_readlane_b32 s0, v253, 6
	s_movk_i32 s1, 0x300
	v_add_u32_e32 v43, s0, v142
	v_add_u32_e32 v56, s0, v122
	v_mov_b32_e32 v44, s94
	v_mov_b32_e32 v45, s95
	v_add_co_u32_e32 v44, vcc, v44, v147
	s_nop 0
	v_addc_co_u32_e32 v45, vcc, 0, v45, vcc
	s_and_saveexec_b64 s[2:3], s[70:71]
	v_mad_u64_u32 v[58:59], s[98:99], v56, 24, s[88:89]
	global_store_dword v[58:59], v36, off
	s_or_b64 exec, exec, s[2:3]
	s_branch .LaT_fla
; __device__ __forceinline__ unsigned pk2(float lo, float hi) { unsigned r; asm("v_cvt_pk_bf16_f32 %0, %1, %2" : "=v"(r) : "v"(lo), "v"(hi)); return r; }
; __device__ __forceinline__ float bflo(unsigned w) { return __uint_as_float(w << 16); }
; __device__ __forceinline__ float bfhi(unsigned w) { return __uint_as_float(w & 0xffff0000u); }
; __device__ __forceinline__ float fexp2(float x) { return __builtin_amdgcn_exp2f(x); }
; __device__ __forceinline__ void attnA_unit(const Args& a, int unit, LAS unsigned char* lds) {
;     ...
;             } else {
;                 const float l1 = LSE[tokg * 6 + hh], l2 = LSE[((size_t)MTOK + tokg) * 6 + hh];
;                 const float mx = fmaxf(lse, fmaxf(l1, l2));
;                 const float w1 = fexp2(l1 - mx), w2 = fexp2(l2 - mx), w3 = fexp2(lse - mx);
;                 const float wi = 1.0f / (w1 + w2 + w3);
;                 const float c1 = w1 * wi, c2 = w2 * wi, c3 = w3 * wi * inv;
;                 const bf16_t* p1 = OA + tokg * 384 + 64 * hh; const bf16_t* p2 = OA + ((size_t)MTOK + tokg) * 384 + 64 * hh;
;                 bf16_t* op = MIX + tokg * DM + 64 * hh;
; #pragma unroll
;                 for (int dt = 0; dt < 2; ++dt)
; #pragma unroll
;                     for (int g = 0; g < 4; ++g) {
;                         const f32x16& o = dt ? o1 : o0;
;                         const int d = 32 * dt + 8 * g + 4 * h;
;                         const u32x2 a1 = *(const u32x2*)(p1 + d), a2 = *(const u32x2*)(p2 + d);
;                         const float r0 = c1 * bflo(a1.x) + c2 * bflo(a2.x) + c3 * o[4 * g], r1 = c1 * bfhi(a1.x) + c2 * bfhi(a2.x) + c3 * o[4 * g + 1];
;                         const float r2 = c1 * bflo(a1.y) + c2 * bflo(a2.y) + c3 * o[4 * g + 2], r3 = c1 * bfhi(a1.y) + c2 * bfhi(a2.y) + c3 * o[4 * g + 3];
;                         u32x2 w; w.x = pk2(r0, r1); w.y = pk2(r2, r3);
;                         *(u32x2*)(op + d) = w;
;                     }
.LaT_mga:
	v_mad_u64_u32 v[58:59], s[98:99], v122, 24, s[88:89]
	global_load_dword v103, v[58:59], off
	v_add_co_u32_e32 v58, vcc, 0x180000, v58
	s_nop 0
	v_addc_co_u32_e32 v59, vcc, 0, v59, vcc
	global_load_dword v104, v[58:59], off
	v_mov_b32_e32 v58, s94
	v_mov_b32_e32 v59, s95
	v_add_co_u32_e32 v58, vcc, v58, v194
	s_movk_i32 s1, 0x300
	v_addc_co_u32_e32 v59, vcc, 0, v59, vcc
	v_mov_b32_e32 v43, v142
	v_mad_u64_u32 v[60:61], s[98:99], v43, s1, v[58:59]
	s_add_i32 m0, s32, 0x0
	s_nop 0
	global_load_lds_dwordx4 v[60:61], off
	v_add_u32_e32 v43, s80, v43
	v_mad_u64_u32 v[60:61], s[98:99], v43, s1, v[58:59]
	s_add_i32 m0, s32, 0x400
	s_nop 0
	global_load_lds_dwordx4 v[60:61], off
	v_add_u32_e32 v43, s80, v43
	v_mad_u64_u32 v[60:61], s[98:99], v43, s1, v[58:59]
	s_add_i32 m0, s32, 0x800
	s_nop 0
	global_load_lds_dwordx4 v[60:61], off
	v_add_u32_e32 v43, s80, v43
	v_mad_u64_u32 v[60:61], s[98:99], v43, s1, v[58:59]
	s_add_i32 m0, s32, 0xc00
	s_nop 0
	global_load_lds_dwordx4 v[60:61], off
	v_add_u32_e32 v43, 0x10000, v142
	v_mad_u64_u32 v[60:61], s[98:99], v43, s1, v[58:59]
	s_add_i32 m0, s32, 0x1000
	s_nop 0
	global_load_lds_dwordx4 v[60:61], off
	v_add_u32_e32 v43, s80, v43
	v_mad_u64_u32 v[60:61], s[98:99], v43, s1, v[58:59]
	s_add_i32 m0, s32, 0x1400
	s_nop 0
	global_load_lds_dwordx4 v[60:61], off
	v_add_u32_e32 v43, s80, v43
	v_mad_u64_u32 v[60:61], s[98:99], v43, s1, v[58:59]
	s_add_i32 m0, s32, 0x1800
	s_nop 0
	global_load_lds_dwordx4 v[60:61], off
	v_add_u32_e32 v43, s80, v43
	v_mad_u64_u32 v[60:61], s[98:99], v43, s1, v[58:59]
	s_add_i32 m0, s32, 0x1c00
	s_nop 0
	global_load_lds_dwordx4 v[60:61], off
	s_waitcnt vmcnt(0)
	v_xor_b32_e32 v41, 0x0, v40
	ds_read_b64 v[160:161], v41
	ds_read_b64 v[176:177], v41 offset:4096
	v_xor_b32_e32 v41, 0x10, v40
	ds_read_b64 v[162:163], v41
	ds_read_b64 v[178:179], v41 offset:4096
	v_xor_b32_e32 v41, 0x20, v40
	ds_read_b64 v[164:165], v41
	ds_read_b64 v[180:181], v41 offset:4096
	v_xor_b32_e32 v41, 0x30, v40
	ds_read_b64 v[166:167], v41
	ds_read_b64 v[182:183], v41 offset:4096
	v_xor_b32_e32 v41, 0x40, v40
	ds_read_b64 v[168:169], v41
	ds_read_b64 v[184:185], v41 offset:4096
	v_xor_b32_e32 v41, 0x50, v40
	ds_read_b64 v[170:171], v41
	ds_read_b64 v[186:187], v41 offset:4096
	v_xor_b32_e32 v41, 0x60, v40
	ds_read_b64 v[172:173], v41
	ds_read_b64 v[188:189], v41 offset:4096
	v_xor_b32_e32 v41, 0x70, v40
	ds_read_b64 v[174:175], v41
	ds_read_b64 v[190:191], v41 offset:4096
	v_max3_f32 v96, v36, v103, v104
	v_sub_f32_e32 v97, v103, v96
	v_sub_f32_e32 v98, v104, v96
	v_sub_f32_e32 v99, v36, v96
	v_exp_f32_e32 v97, v97
	v_exp_f32_e32 v98, v98
	v_exp_f32_e32 v99, v99
	s_nop 0
	v_add_f32_e32 v105, v97, v98
	v_add_f32_e32 v105, v99, v105
	v_div_scale_f32 v35, s[0:1], v105, v105, 1.0
	v_rcp_f32_e32 v37, v35
	v_div_scale_f32 v38, vcc, 1.0, v105, 1.0
	v_fma_f32 v62, -v35, v37, 1.0
	v_fmac_f32_e32 v37, v62, v37
	v_mul_f32_e32 v62, v38, v37
	v_fma_f32 v106, -v35, v62, v38
	v_fmac_f32_e32 v62, v106, v37
	v_fma_f32 v35, -v35, v62, v38
	v_div_fmas_f32 v35, v35, v37, v62
	v_div_fixup_f32 v106, v35, v105, 1.0
	v_mul_f32_e32 v100, v97, v106
	v_mul_f32_e32 v101, v98, v106
	v_mul_f32_e32 v102, v99, v106
	v_mul_f32_e32 v102, v33, v102
	s_waitcnt lgkmcnt(0)
	v_lshlrev_b32_e32 v52, 16, v160
	v_lshlrev_b32_e32 v53, 16, v176
	v_mul_f32_e32 v52, v100, v52
	v_mul_f32_e32 v54, v102, v16
	v_fmac_f32_e32 v52, v101, v53
	v_add_f32_e32 v54, v52, v54
	v_and_b32_e32 v52, 0xffff0000, v160
	v_and_b32_e32 v53, 0xffff0000, v176
	v_mul_f32_e32 v52, v100, v52
	v_mul_f32_e32 v55, v102, v17
	v_fmac_f32_e32 v52, v101, v53
	v_add_f32_e32 v55, v52, v55
	v_lshlrev_b32_e32 v52, 16, v161
	v_lshlrev_b32_e32 v53, 16, v177
	v_mul_f32_e32 v52, v100, v52
	v_mul_f32_e32 v56, v102, v18
	v_fmac_f32_e32 v52, v101, v53
	v_add_f32_e32 v56, v52, v56
	v_and_b32_e32 v52, 0xffff0000, v161
	v_and_b32_e32 v53, 0xffff0000, v177
	v_mul_f32_e32 v52, v100, v52
	v_mul_f32_e32 v57, v102, v19
	v_fmac_f32_e32 v52, v101, v53
	v_add_f32_e32 v57, v52, v57
	v_cvt_pk_bf16_f32 v48, v54, v55
	v_cvt_pk_bf16_f32 v49, v56, v57
	v_xor_b32_e32 v41, 0x0, v40
	ds_write_b64 v41, v[48:49]
	v_lshlrev_b32_e32 v52, 16, v162
	v_lshlrev_b32_e32 v53, 16, v178
	v_mul_f32_e32 v52, v100, v52
	v_mul_f32_e32 v54, v102, v20
	v_fmac_f32_e32 v52, v101, v53
	v_add_f32_e32 v54, v52, v54
	v_and_b32_e32 v52, 0xffff0000, v162
	v_and_b32_e32 v53, 0xffff0000, v178
	v_mul_f32_e32 v52, v100, v52
	v_mul_f32_e32 v55, v102, v21
	v_fmac_f32_e32 v52, v101, v53
	v_add_f32_e32 v55, v52, v55
	v_lshlrev_b32_e32 v52, 16, v163
	v_lshlrev_b32_e32 v53, 16, v179
	v_mul_f32_e32 v52, v100, v52
	v_mul_f32_e32 v56, v102, v22
	v_fmac_f32_e32 v52, v101, v53
	v_add_f32_e32 v56, v52, v56
	v_and_b32_e32 v52, 0xffff0000, v163
	v_and_b32_e32 v53, 0xffff0000, v179
	v_mul_f32_e32 v52, v100, v52
	v_mul_f32_e32 v57, v102, v23
	v_fmac_f32_e32 v52, v101, v53
	v_add_f32_e32 v57, v52, v57
	v_cvt_pk_bf16_f32 v50, v54, v55
	v_cvt_pk_bf16_f32 v51, v56, v57
	v_xor_b32_e32 v41, 0x10, v40
	ds_write_b64 v41, v[50:51]
	v_lshlrev_b32_e32 v52, 16, v164
	v_lshlrev_b32_e32 v53, 16, v180
	v_mul_f32_e32 v52, v100, v52
	v_mul_f32_e32 v54, v102, v24
	v_fmac_f32_e32 v52, v101, v53
	v_add_f32_e32 v54, v52, v54
	v_and_b32_e32 v52, 0xffff0000, v164
	v_and_b32_e32 v53, 0xffff0000, v180
	v_mul_f32_e32 v52, v100, v52
	v_mul_f32_e32 v55, v102, v25
	v_fmac_f32_e32 v52, v101, v53
	v_add_f32_e32 v55, v52, v55
	v_lshlrev_b32_e32 v52, 16, v165
	v_lshlrev_b32_e32 v53, 16, v181
	v_mul_f32_e32 v52, v100, v52
	v_mul_f32_e32 v56, v102, v26
	v_fmac_f32_e32 v52, v101, v53
	v_add_f32_e32 v56, v52, v56
	v_and_b32_e32 v52, 0xffff0000, v165
	v_and_b32_e32 v53, 0xffff0000, v181
; __device__ __forceinline__ unsigned pk2(float lo, float hi) { unsigned r; asm("v_cvt_pk_bf16_f32 %0, %1, %2" : "=v"(r) : "v"(lo), "v"(hi)); return r; }
; __device__ __forceinline__ float bflo(unsigned w) { return __uint_as_float(w << 16); }
; __device__ __forceinline__ float bfhi(unsigned w) { return __uint_as_float(w & 0xffff0000u); }
; __device__ __forceinline__ void attnA_unit(const Args& a, int unit, LAS unsigned char* lds) {
;     ...
; #pragma unroll
;                 for (int dt = 0; dt < 2; ++dt)
; #pragma unroll
;                     for (int g = 0; g < 4; ++g) {
;                         const f32x16& o = dt ? o1 : o0;
;                         const int d = 32 * dt + 8 * g + 4 * h;
;                         const u32x2 a1 = *(const u32x2*)(p1 + d), a2 = *(const u32x2*)(p2 + d);
;                         const float r0 = c1 * bflo(a1.x) + c2 * bflo(a2.x) + c3 * o[4 * g], r1 = c1 * bfhi(a1.x) + c2 * bfhi(a2.x) + c3 * o[4 * g + 1];
;                         const float r2 = c1 * bflo(a1.y) + c2 * bflo(a2.y) + c3 * o[4 * g + 2], r3 = c1 * bfhi(a1.y) + c2 * bfhi(a2.y) + c3 * o[4 * g + 3];
;                         u32x2 w; w.x = pk2(r0, r1); w.y = pk2(r2, r3);
;                         *(u32x2*)(op + d) = w;
;                     }
	v_mul_f32_e32 v52, v100, v52
	v_mul_f32_e32 v57, v102, v27
	v_fmac_f32_e32 v52, v101, v53
	v_add_f32_e32 v57, v52, v57
	v_cvt_pk_bf16_f32 v48, v54, v55
	v_cvt_pk_bf16_f32 v49, v56, v57
	v_xor_b32_e32 v41, 0x20, v40
	ds_write_b64 v41, v[48:49]
	v_lshlrev_b32_e32 v52, 16, v166
	v_lshlrev_b32_e32 v53, 16, v182
	v_mul_f32_e32 v52, v100, v52
	v_mul_f32_e32 v54, v102, v28
	v_fmac_f32_e32 v52, v101, v53
	v_add_f32_e32 v54, v52, v54
	v_and_b32_e32 v52, 0xffff0000, v166
	v_and_b32_e32 v53, 0xffff0000, v182
	v_mul_f32_e32 v52, v100, v52
	v_mul_f32_e32 v55, v102, v29
	v_fmac_f32_e32 v52, v101, v53
	v_add_f32_e32 v55, v52, v55
	v_lshlrev_b32_e32 v52, 16, v167
	v_lshlrev_b32_e32 v53, 16, v183
	v_mul_f32_e32 v52, v100, v52
	v_mul_f32_e32 v56, v102, v30
	v_fmac_f32_e32 v52, v101, v53
	v_add_f32_e32 v56, v52, v56
	v_and_b32_e32 v52, 0xffff0000, v167
	v_and_b32_e32 v53, 0xffff0000, v183
	v_mul_f32_e32 v52, v100, v52
	v_mul_f32_e32 v57, v102, v31
	v_fmac_f32_e32 v52, v101, v53
	v_add_f32_e32 v57, v52, v57
	v_cvt_pk_bf16_f32 v50, v54, v55
	v_cvt_pk_bf16_f32 v51, v56, v57
	v_xor_b32_e32 v41, 0x30, v40
	ds_write_b64 v41, v[50:51]
	v_lshlrev_b32_e32 v52, 16, v168
	v_lshlrev_b32_e32 v53, 16, v184
	v_mul_f32_e32 v52, v100, v52
	v_mul_f32_e32 v54, v102, v0
	v_fmac_f32_e32 v52, v101, v53
	v_add_f32_e32 v54, v52, v54
	v_and_b32_e32 v52, 0xffff0000, v168
	v_and_b32_e32 v53, 0xffff0000, v184
	v_mul_f32_e32 v52, v100, v52
	v_mul_f32_e32 v55, v102, v1
	v_fmac_f32_e32 v52, v101, v53
	v_add_f32_e32 v55, v52, v55
	v_lshlrev_b32_e32 v52, 16, v169
	v_lshlrev_b32_e32 v53, 16, v185
	v_mul_f32_e32 v52, v100, v52
	v_mul_f32_e32 v56, v102, v2
	v_fmac_f32_e32 v52, v101, v53
	v_add_f32_e32 v56, v52, v56
	v_and_b32_e32 v52, 0xffff0000, v169
	v_and_b32_e32 v53, 0xffff0000, v185
	v_mul_f32_e32 v52, v100, v52
	v_mul_f32_e32 v57, v102, v3
	v_fmac_f32_e32 v52, v101, v53
	v_add_f32_e32 v57, v52, v57
	v_cvt_pk_bf16_f32 v48, v54, v55
	v_cvt_pk_bf16_f32 v49, v56, v57
	v_xor_b32_e32 v41, 0x40, v40
	ds_write_b64 v41, v[48:49]
	v_lshlrev_b32_e32 v52, 16, v170
	v_lshlrev_b32_e32 v53, 16, v186
	v_mul_f32_e32 v52, v100, v52
	v_mul_f32_e32 v54, v102, v4
	v_fmac_f32_e32 v52, v101, v53
	v_add_f32_e32 v54, v52, v54
	v_and_b32_e32 v52, 0xffff0000, v170
	v_and_b32_e32 v53, 0xffff0000, v186
	v_mul_f32_e32 v52, v100, v52
	v_mul_f32_e32 v55, v102, v5
	v_fmac_f32_e32 v52, v101, v53
	v_add_f32_e32 v55, v52, v55
	v_lshlrev_b32_e32 v52, 16, v171
	v_lshlrev_b32_e32 v53, 16, v187
	v_mul_f32_e32 v52, v100, v52
	v_mul_f32_e32 v56, v102, v6
	v_fmac_f32_e32 v52, v101, v53
	v_add_f32_e32 v56, v52, v56
	v_and_b32_e32 v52, 0xffff0000, v171
	v_and_b32_e32 v53, 0xffff0000, v187
	v_mul_f32_e32 v52, v100, v52
	v_mul_f32_e32 v57, v102, v7
	v_fmac_f32_e32 v52, v101, v53
	v_add_f32_e32 v57, v52, v57
	v_cvt_pk_bf16_f32 v50, v54, v55
	v_cvt_pk_bf16_f32 v51, v56, v57
	v_xor_b32_e32 v41, 0x50, v40
	ds_write_b64 v41, v[50:51]
	v_lshlrev_b32_e32 v52, 16, v172
	v_lshlrev_b32_e32 v53, 16, v188
	v_mul_f32_e32 v52, v100, v52
	v_mul_f32_e32 v54, v102, v8
	v_fmac_f32_e32 v52, v101, v53
	v_add_f32_e32 v54, v52, v54
	v_and_b32_e32 v52, 0xffff0000, v172
	v_and_b32_e32 v53, 0xffff0000, v188
	v_mul_f32_e32 v52, v100, v52
	v_mul_f32_e32 v55, v102, v9
	v_fmac_f32_e32 v52, v101, v53
	v_add_f32_e32 v55, v52, v55
	v_lshlrev_b32_e32 v52, 16, v173
	v_lshlrev_b32_e32 v53, 16, v189
	v_mul_f32_e32 v52, v100, v52
	v_mul_f32_e32 v56, v102, v10
	v_fmac_f32_e32 v52, v101, v53
	v_add_f32_e32 v56, v52, v56
	v_and_b32_e32 v52, 0xffff0000, v173
	v_and_b32_e32 v53, 0xffff0000, v189
	v_mul_f32_e32 v52, v100, v52
	v_mul_f32_e32 v57, v102, v11
	v_fmac_f32_e32 v52, v101, v53
	v_add_f32_e32 v57, v52, v57
	v_cvt_pk_bf16_f32 v48, v54, v55
	v_cvt_pk_bf16_f32 v49, v56, v57
	v_xor_b32_e32 v41, 0x60, v40
	ds_write_b64 v41, v[48:49]
	v_lshlrev_b32_e32 v52, 16, v174
	v_lshlrev_b32_e32 v53, 16, v190
	v_mul_f32_e32 v52, v100, v52
	v_mul_f32_e32 v54, v102, v12
	v_fmac_f32_e32 v52, v101, v53
	v_add_f32_e32 v54, v52, v54
	v_and_b32_e32 v52, 0xffff0000, v174
	v_and_b32_e32 v53, 0xffff0000, v190
	v_mul_f32_e32 v52, v100, v52
	v_mul_f32_e32 v55, v102, v13
	v_fmac_f32_e32 v52, v101, v53
	v_add_f32_e32 v55, v52, v55
	v_lshlrev_b32_e32 v52, 16, v175
	v_lshlrev_b32_e32 v53, 16, v191
	v_mul_f32_e32 v52, v100, v52
	v_mul_f32_e32 v56, v102, v14
	v_fmac_f32_e32 v52, v101, v53
	v_add_f32_e32 v56, v52, v56
	v_and_b32_e32 v52, 0xffff0000, v175
	v_and_b32_e32 v53, 0xffff0000, v191
	v_mul_f32_e32 v52, v100, v52
	v_mul_f32_e32 v57, v102, v15
	v_fmac_f32_e32 v52, v101, v53
	v_add_f32_e32 v57, v52, v57
	v_cvt_pk_bf16_f32 v50, v54, v55
	v_cvt_pk_bf16_f32 v51, v56, v57
	v_xor_b32_e32 v41, 0x70, v40
	ds_write_b64 v41, v[50:51]
	s_movk_i32 s1, 0x800
	v_mov_b32_e32 v43, v142
	v_sub_u32_e32 v46, v147, v154
	v_ashrrev_i32_e32 v47, 31, v46
	v_add_co_u32_e32 v44, vcc, v118, v46
	s_nop 0
	v_addc_co_u32_e32 v45, vcc, v119, v47, vcc
; __device__ __forceinline__ unsigned pk2(float lo, float hi) { unsigned r; asm("v_cvt_pk_bf16_f32 %0, %1, %2" : "=v"(r) : "v"(lo), "v"(hi)); return r; }
; __device__ __forceinline__ void attnA_unit(const Args& a, int unit, LAS unsigned char* lds) {
;     ...
;             const float lt = l + __shfl_xor(l, 32);
;             const float inv = 1.0f / lt, lse = m + __builtin_amdgcn_logf(lt);
;             const size_t tokg = (size_t)b * SEQ + tq;
;             if (pidx < 2) {
;                 bf16_t* op = OA + ((size_t)pidx * MTOK + tokg) * 384 + 64 * hh;
; #pragma unroll
;                 for (int dt = 0; dt < 2; ++dt)
; #pragma unroll
;                     for (int g = 0; g < 4; ++g) {
;                         const f32x16& o = dt ? o1 : o0;
;                         u32x2 w; w.x = pk2(o[4 * g] * inv, o[4 * g + 1] * inv); w.y = pk2(o[4 * g + 2] * inv, o[4 * g + 3] * inv);
;                         *(u32x2*)(op + 32 * dt + 8 * g + 4 * h) = w;
;                     }
;                 if (h == 0) LSE[((size_t)pidx * MTOK + tokg) * 6 + hh] = lse;
.LaT_fla:
	v_add_u32_e32 v41, s32, v193
	s_waitcnt lgkmcnt(0)
	ds_read_b128 v[160:163], v41
	ds_read_b128 v[164:167], v41 offset:1024
	ds_read_b128 v[168:171], v41 offset:2048
	ds_read_b128 v[172:175], v41 offset:3072
	v_mad_u64_u32 v[46:47], s[98:99], v43, s1, v[44:45]
	s_waitcnt lgkmcnt(3)
	global_store_dwordx4 v[46:47], v[160:163], off
	v_add_u32_e32 v43, s80, v43
	v_mad_u64_u32 v[58:59], s[98:99], v43, s1, v[44:45]
	s_waitcnt lgkmcnt(2)
	global_store_dwordx4 v[58:59], v[164:167], off
	v_add_u32_e32 v43, s80, v43
	v_mad_u64_u32 v[46:47], s[98:99], v43, s1, v[44:45]
	s_waitcnt lgkmcnt(1)
	global_store_dwordx4 v[46:47], v[168:171], off
	v_add_u32_e32 v43, s80, v43
	v_mad_u64_u32 v[58:59], s[98:99], v43, s1, v[44:45]
	s_waitcnt lgkmcnt(0)
	global_store_dwordx4 v[58:59], v[172:175], off
	s_lshl_b32 s32, s83, 13
	s_add_i32 s32, s32, 0x2000
	v_mov_b32_e32 v39, v213
	s_nop 1
	v_permlane32_swap_b32_e32 v39, v213
	v_add_f32_e32 v63, v213, v39
	v_add_u32_e32 v40, s32, v192
	v_log_f32_e32 v34, v63
	v_div_scale_f32 v35, s[0:1], v63, v63, 1.0
	v_rcp_f32_e32 v37, v35
	v_div_scale_f32 v38, vcc, 1.0, v63, 1.0
	v_fma_f32 v62, -v35, v37, 1.0
	v_fmac_f32_e32 v37, v62, v37
	v_mul_f32_e32 v62, v38, v37
	v_fma_f32 v33, -v35, v62, v38
	v_fmac_f32_e32 v62, v33, v37
	v_fma_f32 v35, -v35, v62, v38
	v_div_fmas_f32 v35, v35, v37, v62
	v_div_fixup_f32 v33, v35, v63, 1.0
	v_add_f32_e32 v36, v212, v34
	s_lshl_b32 s80, 8, s73
	s_and_b64 vcc, exec, s[90:91]
	s_cbranch_vccz .LaT_mgb
	v_mul_f32_e32 v52, v80, v33
	v_mul_f32_e32 v53, v81, v33
	v_mul_f32_e32 v54, v82, v33
	v_mul_f32_e32 v55, v83, v33
	v_cvt_pk_bf16_f32 v48, v52, v53
	v_cvt_pk_bf16_f32 v49, v54, v55
	v_xor_b32_e32 v41, 0x0, v40
	ds_write_b64 v41, v[48:49]
	v_mul_f32_e32 v52, v84, v33
	v_mul_f32_e32 v53, v85, v33
	v_mul_f32_e32 v54, v86, v33
	v_mul_f32_e32 v55, v87, v33
	v_cvt_pk_bf16_f32 v50, v52, v53
	v_cvt_pk_bf16_f32 v51, v54, v55
	v_xor_b32_e32 v41, 0x10, v40
	ds_write_b64 v41, v[50:51]
	v_mul_f32_e32 v52, v88, v33
	v_mul_f32_e32 v53, v89, v33
	v_mul_f32_e32 v54, v90, v33
	v_mul_f32_e32 v55, v91, v33
	v_cvt_pk_bf16_f32 v48, v52, v53
	v_cvt_pk_bf16_f32 v49, v54, v55
	v_xor_b32_e32 v41, 0x20, v40
	ds_write_b64 v41, v[48:49]
	v_mul_f32_e32 v52, v92, v33
	v_mul_f32_e32 v53, v93, v33
	v_mul_f32_e32 v54, v94, v33
	v_mul_f32_e32 v55, v95, v33
	v_cvt_pk_bf16_f32 v50, v52, v53
	v_cvt_pk_bf16_f32 v51, v54, v55
	v_xor_b32_e32 v41, 0x30, v40
	ds_write_b64 v41, v[50:51]
	v_mul_f32_e32 v52, v64, v33
	v_mul_f32_e32 v53, v65, v33
	v_mul_f32_e32 v54, v66, v33
	v_mul_f32_e32 v55, v67, v33
	v_cvt_pk_bf16_f32 v48, v52, v53
	v_cvt_pk_bf16_f32 v49, v54, v55
	v_xor_b32_e32 v41, 0x40, v40
	ds_write_b64 v41, v[48:49]
	v_mul_f32_e32 v52, v68, v33
	v_mul_f32_e32 v53, v69, v33
	v_mul_f32_e32 v54, v70, v33
	v_mul_f32_e32 v55, v71, v33
	v_cvt_pk_bf16_f32 v50, v52, v53
	v_cvt_pk_bf16_f32 v51, v54, v55
	v_xor_b32_e32 v41, 0x50, v40
	ds_write_b64 v41, v[50:51]
	v_mul_f32_e32 v52, v72, v33
	v_mul_f32_e32 v53, v73, v33
	v_mul_f32_e32 v54, v74, v33
	v_mul_f32_e32 v55, v75, v33
	v_cvt_pk_bf16_f32 v48, v52, v53
	v_cvt_pk_bf16_f32 v49, v54, v55
	v_xor_b32_e32 v41, 0x60, v40
	ds_write_b64 v41, v[48:49]
	v_mul_f32_e32 v52, v76, v33
	v_mul_f32_e32 v53, v77, v33
	v_mul_f32_e32 v54, v78, v33
	v_mul_f32_e32 v55, v79, v33
	v_cvt_pk_bf16_f32 v50, v52, v53
	v_cvt_pk_bf16_f32 v51, v54, v55
	v_xor_b32_e32 v41, 0x70, v40
	ds_write_b64 v41, v[50:51]
	v_readlane_b32 s0, v253, 6
	s_movk_i32 s1, 0x300
	v_add_u32_e32 v43, s0, v224
	v_add_u32_e32 v56, s0, v216
	v_mov_b32_e32 v44, s94
	v_mov_b32_e32 v45, s95
	v_add_co_u32_e32 v44, vcc, v44, v147
	s_nop 0
	v_addc_co_u32_e32 v45, vcc, 0, v45, vcc
	s_and_saveexec_b64 s[2:3], s[70:71]
	v_mad_u64_u32 v[58:59], s[98:99], v56, 24, s[88:89]
	global_store_dword v[58:59], v36, off
	s_or_b64 exec, exec, s[2:3]
	s_branch .LaT_flb
.LaT_mgb:
	v_mad_u64_u32 v[58:59], s[98:99], v216, 24, s[88:89]
	global_load_dword v103, v[58:59], off
	v_add_co_u32_e32 v58, vcc, 0x180000, v58
	s_nop 0
	v_addc_co_u32_e32 v59, vcc, 0, v59, vcc
	global_load_dword v104, v[58:59], off
	v_mov_b32_e32 v58, s94
	v_mov_b32_e32 v59, s95
	v_add_co_u32_e32 v58, vcc, v58, v194
	s_movk_i32 s1, 0x300
	v_addc_co_u32_e32 v59, vcc, 0, v59, vcc
	v_mov_b32_e32 v43, v224
	v_mad_u64_u32 v[60:61], s[98:99], v43, s1, v[58:59]
	s_add_i32 m0, s32, 0x0
	s_nop 0
	global_load_lds_dwordx4 v[60:61], off
	v_add_u32_e32 v43, s80, v43
	v_mad_u64_u32 v[60:61], s[98:99], v43, s1, v[58:59]
	s_add_i32 m0, s32, 0x400
	s_nop 0
	global_load_lds_dwordx4 v[60:61], off
	v_add_u32_e32 v43, s80, v43
	v_mad_u64_u32 v[60:61], s[98:99], v43, s1, v[58:59]
	s_add_i32 m0, s32, 0x800
	s_nop 0
	global_load_lds_dwordx4 v[60:61], off
	v_add_u32_e32 v43, s80, v43
	v_mad_u64_u32 v[60:61], s[98:99], v43, s1, v[58:59]
	s_add_i32 m0, s32, 0xc00
	s_nop 0
	global_load_lds_dwordx4 v[60:61], off
	v_add_u32_e32 v43, 0x10000, v224
	v_mad_u64_u32 v[60:61], s[98:99], v43, s1, v[58:59]
	s_add_i32 m0, s32, 0x1000
	s_nop 0
	global_load_lds_dwordx4 v[60:61], off
	v_add_u32_e32 v43, s80, v43
	v_mad_u64_u32 v[60:61], s[98:99], v43, s1, v[58:59]
	s_add_i32 m0, s32, 0x1400
	s_nop 0
	global_load_lds_dwordx4 v[60:61], off
	v_add_u32_e32 v43, s80, v43
	v_mad_u64_u32 v[60:61], s[98:99], v43, s1, v[58:59]
	s_add_i32 m0, s32, 0x1800
	s_nop 0
	global_load_lds_dwordx4 v[60:61], off
	v_add_u32_e32 v43, s80, v43
	v_mad_u64_u32 v[60:61], s[98:99], v43, s1, v[58:59]
	s_add_i32 m0, s32, 0x1c00
	s_nop 0
	global_load_lds_dwordx4 v[60:61], off
	s_waitcnt vmcnt(0)
; __device__ __forceinline__ unsigned pk2(float lo, float hi) { unsigned r; asm("v_cvt_pk_bf16_f32 %0, %1, %2" : "=v"(r) : "v"(lo), "v"(hi)); return r; }
; __device__ __forceinline__ float bflo(unsigned w) { return __uint_as_float(w << 16); }
; __device__ __forceinline__ float bfhi(unsigned w) { return __uint_as_float(w & 0xffff0000u); }
; __device__ __forceinline__ float fexp2(float x) { return __builtin_amdgcn_exp2f(x); }
; __device__ __forceinline__ void attnA_unit(const Args& a, int unit, LAS unsigned char* lds) {
;     ...
;             } else {
;                 const float l1 = LSE[tokg * 6 + hh], l2 = LSE[((size_t)MTOK + tokg) * 6 + hh];
;                 const float mx = fmaxf(lse, fmaxf(l1, l2));
;                 const float w1 = fexp2(l1 - mx), w2 = fexp2(l2 - mx), w3 = fexp2(lse - mx);
;                 const float wi = 1.0f / (w1 + w2 + w3);
;                 const float c1 = w1 * wi, c2 = w2 * wi, c3 = w3 * wi * inv;
;                 const bf16_t* p1 = OA + tokg * 384 + 64 * hh; const bf16_t* p2 = OA + ((size_t)MTOK + tokg) * 384 + 64 * hh;
;                 bf16_t* op = MIX + tokg * DM + 64 * hh;
; #pragma unroll
;                 for (int dt = 0; dt < 2; ++dt)
; #pragma unroll
;                     for (int g = 0; g < 4; ++g) {
;                         const f32x16& o = dt ? o1 : o0;
;                         const int d = 32 * dt + 8 * g + 4 * h;
;                         const u32x2 a1 = *(const u32x2*)(p1 + d), a2 = *(const u32x2*)(p2 + d);
;                         const float r0 = c1 * bflo(a1.x) + c2 * bflo(a2.x) + c3 * o[4 * g], r1 = c1 * bfhi(a1.x) + c2 * bfhi(a2.x) + c3 * o[4 * g + 1];
;                         const float r2 = c1 * bflo(a1.y) + c2 * bflo(a2.y) + c3 * o[4 * g + 2], r3 = c1 * bfhi(a1.y) + c2 * bfhi(a2.y) + c3 * o[4 * g + 3];
;                         u32x2 w; w.x = pk2(r0, r1); w.y = pk2(r2, r3);
;                         *(u32x2*)(op + d) = w;
;                     }
	v_xor_b32_e32 v41, 0x0, v40
	ds_read_b64 v[160:161], v41
	ds_read_b64 v[176:177], v41 offset:4096
	v_xor_b32_e32 v41, 0x10, v40
	ds_read_b64 v[162:163], v41
	ds_read_b64 v[178:179], v41 offset:4096
	v_xor_b32_e32 v41, 0x20, v40
	ds_read_b64 v[164:165], v41
	ds_read_b64 v[180:181], v41 offset:4096
	v_xor_b32_e32 v41, 0x30, v40
	ds_read_b64 v[166:167], v41
	ds_read_b64 v[182:183], v41 offset:4096
	v_xor_b32_e32 v41, 0x40, v40
	ds_read_b64 v[168:169], v41
	ds_read_b64 v[184:185], v41 offset:4096
	v_xor_b32_e32 v41, 0x50, v40
	ds_read_b64 v[170:171], v41
	ds_read_b64 v[186:187], v41 offset:4096
	v_xor_b32_e32 v41, 0x60, v40
	ds_read_b64 v[172:173], v41
	ds_read_b64 v[188:189], v41 offset:4096
	v_xor_b32_e32 v41, 0x70, v40
	ds_read_b64 v[174:175], v41
	ds_read_b64 v[190:191], v41 offset:4096
	v_max3_f32 v96, v36, v103, v104
	v_sub_f32_e32 v97, v103, v96
	v_sub_f32_e32 v98, v104, v96
	v_sub_f32_e32 v99, v36, v96
	v_exp_f32_e32 v97, v97
	v_exp_f32_e32 v98, v98
	v_exp_f32_e32 v99, v99
	s_nop 0
	v_add_f32_e32 v105, v97, v98
	v_add_f32_e32 v105, v99, v105
	v_div_scale_f32 v35, s[0:1], v105, v105, 1.0
	v_rcp_f32_e32 v37, v35
	v_div_scale_f32 v38, vcc, 1.0, v105, 1.0
	v_fma_f32 v62, -v35, v37, 1.0
	v_fmac_f32_e32 v37, v62, v37
	v_mul_f32_e32 v62, v38, v37
	v_fma_f32 v106, -v35, v62, v38
	v_fmac_f32_e32 v62, v106, v37
	v_fma_f32 v35, -v35, v62, v38
	v_div_fmas_f32 v35, v35, v37, v62
	v_div_fixup_f32 v106, v35, v105, 1.0
	v_mul_f32_e32 v100, v97, v106
	v_mul_f32_e32 v101, v98, v106
	v_mul_f32_e32 v102, v99, v106
	v_mul_f32_e32 v102, v33, v102
	s_waitcnt lgkmcnt(0)
	v_lshlrev_b32_e32 v52, 16, v160
	v_lshlrev_b32_e32 v53, 16, v176
	v_mul_f32_e32 v52, v100, v52
	v_mul_f32_e32 v54, v102, v80
	v_fmac_f32_e32 v52, v101, v53
	v_add_f32_e32 v54, v52, v54
	v_and_b32_e32 v52, 0xffff0000, v160
	v_and_b32_e32 v53, 0xffff0000, v176
	v_mul_f32_e32 v52, v100, v52
	v_mul_f32_e32 v55, v102, v81
	v_fmac_f32_e32 v52, v101, v53
	v_add_f32_e32 v55, v52, v55
	v_lshlrev_b32_e32 v52, 16, v161
	v_lshlrev_b32_e32 v53, 16, v177
	v_mul_f32_e32 v52, v100, v52
	v_mul_f32_e32 v56, v102, v82
	v_fmac_f32_e32 v52, v101, v53
	v_add_f32_e32 v56, v52, v56
	v_and_b32_e32 v52, 0xffff0000, v161
	v_and_b32_e32 v53, 0xffff0000, v177
	v_mul_f32_e32 v52, v100, v52
	v_mul_f32_e32 v57, v102, v83
	v_fmac_f32_e32 v52, v101, v53
	v_add_f32_e32 v57, v52, v57
	v_cvt_pk_bf16_f32 v48, v54, v55
	v_cvt_pk_bf16_f32 v49, v56, v57
	v_xor_b32_e32 v41, 0x0, v40
	ds_write_b64 v41, v[48:49]
	v_lshlrev_b32_e32 v52, 16, v162
	v_lshlrev_b32_e32 v53, 16, v178
	v_mul_f32_e32 v52, v100, v52
	v_mul_f32_e32 v54, v102, v84
	v_fmac_f32_e32 v52, v101, v53
	v_add_f32_e32 v54, v52, v54
	v_and_b32_e32 v52, 0xffff0000, v162
	v_and_b32_e32 v53, 0xffff0000, v178
	v_mul_f32_e32 v52, v100, v52
	v_mul_f32_e32 v55, v102, v85
	v_fmac_f32_e32 v52, v101, v53
	v_add_f32_e32 v55, v52, v55
	v_lshlrev_b32_e32 v52, 16, v163
	v_lshlrev_b32_e32 v53, 16, v179
	v_mul_f32_e32 v52, v100, v52
	v_mul_f32_e32 v56, v102, v86
	v_fmac_f32_e32 v52, v101, v53
	v_add_f32_e32 v56, v52, v56
	v_and_b32_e32 v52, 0xffff0000, v163
	v_and_b32_e32 v53, 0xffff0000, v179
	v_mul_f32_e32 v52, v100, v52
	v_mul_f32_e32 v57, v102, v87
	v_fmac_f32_e32 v52, v101, v53
	v_add_f32_e32 v57, v52, v57
	v_cvt_pk_bf16_f32 v50, v54, v55
	v_cvt_pk_bf16_f32 v51, v56, v57
	v_xor_b32_e32 v41, 0x10, v40
	ds_write_b64 v41, v[50:51]
	v_lshlrev_b32_e32 v52, 16, v164
	v_lshlrev_b32_e32 v53, 16, v180
	v_mul_f32_e32 v52, v100, v52
	v_mul_f32_e32 v54, v102, v88
	v_fmac_f32_e32 v52, v101, v53
	v_add_f32_e32 v54, v52, v54
	v_and_b32_e32 v52, 0xffff0000, v164
	v_and_b32_e32 v53, 0xffff0000, v180
	v_mul_f32_e32 v52, v100, v52
	v_mul_f32_e32 v55, v102, v89
	v_fmac_f32_e32 v52, v101, v53
	v_add_f32_e32 v55, v52, v55
	v_lshlrev_b32_e32 v52, 16, v165
	v_lshlrev_b32_e32 v53, 16, v181
	v_mul_f32_e32 v52, v100, v52
	v_mul_f32_e32 v56, v102, v90
	v_fmac_f32_e32 v52, v101, v53
	v_add_f32_e32 v56, v52, v56
	v_and_b32_e32 v52, 0xffff0000, v165
	v_and_b32_e32 v53, 0xffff0000, v181
	v_mul_f32_e32 v52, v100, v52
	v_mul_f32_e32 v57, v102, v91
	v_fmac_f32_e32 v52, v101, v53
	v_add_f32_e32 v57, v52, v57
	v_cvt_pk_bf16_f32 v48, v54, v55
	v_cvt_pk_bf16_f32 v49, v56, v57
	v_xor_b32_e32 v41, 0x20, v40
	ds_write_b64 v41, v[48:49]
	v_lshlrev_b32_e32 v52, 16, v166
	v_lshlrev_b32_e32 v53, 16, v182
	v_mul_f32_e32 v52, v100, v52
	v_mul_f32_e32 v54, v102, v92
	v_fmac_f32_e32 v52, v101, v53
	v_add_f32_e32 v54, v52, v54
	v_and_b32_e32 v52, 0xffff0000, v166
	v_and_b32_e32 v53, 0xffff0000, v182
	v_mul_f32_e32 v52, v100, v52
	v_mul_f32_e32 v55, v102, v93
	v_fmac_f32_e32 v52, v101, v53
	v_add_f32_e32 v55, v52, v55
	v_lshlrev_b32_e32 v52, 16, v167
	v_lshlrev_b32_e32 v53, 16, v183
	v_mul_f32_e32 v52, v100, v52
	v_mul_f32_e32 v56, v102, v94
	v_fmac_f32_e32 v52, v101, v53
	v_add_f32_e32 v56, v52, v56
	v_and_b32_e32 v52, 0xffff0000, v167
; __device__ __forceinline__ unsigned pk2(float lo, float hi) { unsigned r; asm("v_cvt_pk_bf16_f32 %0, %1, %2" : "=v"(r) : "v"(lo), "v"(hi)); return r; }
; __device__ __forceinline__ float bflo(unsigned w) { return __uint_as_float(w << 16); }
; __device__ __forceinline__ float bfhi(unsigned w) { return __uint_as_float(w & 0xffff0000u); }
; __device__ __forceinline__ void attnA_unit(const Args& a, int unit, LAS unsigned char* lds) {
;     ...
; #pragma unroll
;                 for (int dt = 0; dt < 2; ++dt)
; #pragma unroll
;                     for (int g = 0; g < 4; ++g) {
;                         const f32x16& o = dt ? o1 : o0;
;                         const int d = 32 * dt + 8 * g + 4 * h;
;                         const u32x2 a1 = *(const u32x2*)(p1 + d), a2 = *(const u32x2*)(p2 + d);
;                         const float r0 = c1 * bflo(a1.x) + c2 * bflo(a2.x) + c3 * o[4 * g], r1 = c1 * bfhi(a1.x) + c2 * bfhi(a2.x) + c3 * o[4 * g + 1];
;                         const float r2 = c1 * bflo(a1.y) + c2 * bflo(a2.y) + c3 * o[4 * g + 2], r3 = c1 * bfhi(a1.y) + c2 * bfhi(a2.y) + c3 * o[4 * g + 3];
;                         u32x2 w; w.x = pk2(r0, r1); w.y = pk2(r2, r3);
;                         *(u32x2*)(op + d) = w;
;                     }
	v_and_b32_e32 v53, 0xffff0000, v183
	v_mul_f32_e32 v52, v100, v52
	v_mul_f32_e32 v57, v102, v95
	v_fmac_f32_e32 v52, v101, v53
	v_add_f32_e32 v57, v52, v57
	v_cvt_pk_bf16_f32 v50, v54, v55
	v_cvt_pk_bf16_f32 v51, v56, v57
	v_xor_b32_e32 v41, 0x30, v40
	ds_write_b64 v41, v[50:51]
	v_lshlrev_b32_e32 v52, 16, v168
	v_lshlrev_b32_e32 v53, 16, v184
	v_mul_f32_e32 v52, v100, v52
	v_mul_f32_e32 v54, v102, v64
	v_fmac_f32_e32 v52, v101, v53
	v_add_f32_e32 v54, v52, v54
	v_and_b32_e32 v52, 0xffff0000, v168
	v_and_b32_e32 v53, 0xffff0000, v184
	v_mul_f32_e32 v52, v100, v52
	v_mul_f32_e32 v55, v102, v65
	v_fmac_f32_e32 v52, v101, v53
	v_add_f32_e32 v55, v52, v55
	v_lshlrev_b32_e32 v52, 16, v169
	v_lshlrev_b32_e32 v53, 16, v185
	v_mul_f32_e32 v52, v100, v52
	v_mul_f32_e32 v56, v102, v66
	v_fmac_f32_e32 v52, v101, v53
	v_add_f32_e32 v56, v52, v56
	v_and_b32_e32 v52, 0xffff0000, v169
	v_and_b32_e32 v53, 0xffff0000, v185
	v_mul_f32_e32 v52, v100, v52
	v_mul_f32_e32 v57, v102, v67
	v_fmac_f32_e32 v52, v101, v53
	v_add_f32_e32 v57, v52, v57
	v_cvt_pk_bf16_f32 v48, v54, v55
	v_cvt_pk_bf16_f32 v49, v56, v57
	v_xor_b32_e32 v41, 0x40, v40
	ds_write_b64 v41, v[48:49]
	v_lshlrev_b32_e32 v52, 16, v170
	v_lshlrev_b32_e32 v53, 16, v186
	v_mul_f32_e32 v52, v100, v52
	v_mul_f32_e32 v54, v102, v68
	v_fmac_f32_e32 v52, v101, v53
	v_add_f32_e32 v54, v52, v54
	v_and_b32_e32 v52, 0xffff0000, v170
	v_and_b32_e32 v53, 0xffff0000, v186
	v_mul_f32_e32 v52, v100, v52
	v_mul_f32_e32 v55, v102, v69
	v_fmac_f32_e32 v52, v101, v53
	v_add_f32_e32 v55, v52, v55
	v_lshlrev_b32_e32 v52, 16, v171
	v_lshlrev_b32_e32 v53, 16, v187
	v_mul_f32_e32 v52, v100, v52
	v_mul_f32_e32 v56, v102, v70
	v_fmac_f32_e32 v52, v101, v53
	v_add_f32_e32 v56, v52, v56
	v_and_b32_e32 v52, 0xffff0000, v171
	v_and_b32_e32 v53, 0xffff0000, v187
	v_mul_f32_e32 v52, v100, v52
	v_mul_f32_e32 v57, v102, v71
	v_fmac_f32_e32 v52, v101, v53
	v_add_f32_e32 v57, v52, v57
	v_cvt_pk_bf16_f32 v50, v54, v55
	v_cvt_pk_bf16_f32 v51, v56, v57
	v_xor_b32_e32 v41, 0x50, v40
	ds_write_b64 v41, v[50:51]
	v_lshlrev_b32_e32 v52, 16, v172
	v_lshlrev_b32_e32 v53, 16, v188
	v_mul_f32_e32 v52, v100, v52
	v_mul_f32_e32 v54, v102, v72
	v_fmac_f32_e32 v52, v101, v53
	v_add_f32_e32 v54, v52, v54
	v_and_b32_e32 v52, 0xffff0000, v172
	v_and_b32_e32 v53, 0xffff0000, v188
	v_mul_f32_e32 v52, v100, v52
	v_mul_f32_e32 v55, v102, v73
	v_fmac_f32_e32 v52, v101, v53
	v_add_f32_e32 v55, v52, v55
	v_lshlrev_b32_e32 v52, 16, v173
	v_lshlrev_b32_e32 v53, 16, v189
	v_mul_f32_e32 v52, v100, v52
	v_mul_f32_e32 v56, v102, v74
	v_fmac_f32_e32 v52, v101, v53
	v_add_f32_e32 v56, v52, v56
	v_and_b32_e32 v52, 0xffff0000, v173
	v_and_b32_e32 v53, 0xffff0000, v189
	v_mul_f32_e32 v52, v100, v52
	v_mul_f32_e32 v57, v102, v75
	v_fmac_f32_e32 v52, v101, v53
	v_add_f32_e32 v57, v52, v57
	v_cvt_pk_bf16_f32 v48, v54, v55
	v_cvt_pk_bf16_f32 v49, v56, v57
	v_xor_b32_e32 v41, 0x60, v40
	ds_write_b64 v41, v[48:49]
	v_lshlrev_b32_e32 v52, 16, v174
	v_lshlrev_b32_e32 v53, 16, v190
	v_mul_f32_e32 v52, v100, v52
	v_mul_f32_e32 v54, v102, v76
	v_fmac_f32_e32 v52, v101, v53
	v_add_f32_e32 v54, v52, v54
	v_and_b32_e32 v52, 0xffff0000, v174
	v_and_b32_e32 v53, 0xffff0000, v190
	v_mul_f32_e32 v52, v100, v52
	v_mul_f32_e32 v55, v102, v77
	v_fmac_f32_e32 v52, v101, v53
	v_add_f32_e32 v55, v52, v55
	v_lshlrev_b32_e32 v52, 16, v175
	v_lshlrev_b32_e32 v53, 16, v191
	v_mul_f32_e32 v52, v100, v52
	v_mul_f32_e32 v56, v102, v78
	v_fmac_f32_e32 v52, v101, v53
	v_add_f32_e32 v56, v52, v56
	v_and_b32_e32 v52, 0xffff0000, v175
	v_and_b32_e32 v53, 0xffff0000, v191
	v_mul_f32_e32 v52, v100, v52
	v_mul_f32_e32 v57, v102, v79
	v_fmac_f32_e32 v52, v101, v53
	v_add_f32_e32 v57, v52, v57
	v_cvt_pk_bf16_f32 v50, v54, v55
	v_cvt_pk_bf16_f32 v51, v56, v57
	v_xor_b32_e32 v41, 0x70, v40
	ds_write_b64 v41, v[50:51]
	s_movk_i32 s1, 0x800
	v_mov_b32_e32 v43, v224
	v_sub_u32_e32 v46, v147, v154
	v_ashrrev_i32_e32 v47, 31, v46
	v_add_co_u32_e32 v44, vcc, v118, v46
	s_nop 0
	v_addc_co_u32_e32 v45, vcc, v119, v47, vcc
.LaT_flb:
	v_add_u32_e32 v41, s32, v193
	s_waitcnt lgkmcnt(0)
	ds_read_b128 v[160:163], v41
	ds_read_b128 v[164:167], v41 offset:1024
	ds_read_b128 v[168:171], v41 offset:2048
	ds_read_b128 v[172:175], v41 offset:3072
	v_mad_u64_u32 v[46:47], s[98:99], v43, s1, v[44:45]
	s_waitcnt lgkmcnt(3)
	global_store_dwordx4 v[46:47], v[160:163], off
	v_add_u32_e32 v43, s80, v43
	v_mad_u64_u32 v[58:59], s[98:99], v43, s1, v[44:45]
	s_waitcnt lgkmcnt(2)
	global_store_dwordx4 v[58:59], v[164:167], off
	v_add_u32_e32 v43, s80, v43
	v_mad_u64_u32 v[46:47], s[98:99], v43, s1, v[44:45]
	s_waitcnt lgkmcnt(1)
	global_store_dwordx4 v[46:47], v[168:171], off
	v_add_u32_e32 v43, s80, v43
	v_mad_u64_u32 v[58:59], s[98:99], v43, s1, v[44:45]
	s_waitcnt lgkmcnt(0)
	global_store_dwordx4 v[58:59], v[172:175], off
	s_branch .LBB0_262
